# grid barrier: first local arriver issues an early buffer_wbl2 so the L2 write-back overlaps stragglers
# speedup vs baseline: 1.0074x; 1.0005x over previous
; __device__ __forceinline__ unsigned xb_ld(unsigned* p)              { return __hip_atomic_load(p, __ATOMIC_RELAXED, __HIP_MEMORY_SCOPE_AGENT); }
; __device__ __forceinline__ unsigned xb_add(unsigned* p, unsigned v) { return __hip_atomic_fetch_add(p, v, __ATOMIC_RELAXED, __HIP_MEMORY_SCOPE_AGENT); }
; #define XB_SPIN(cond, bar) do { unsigned _sp = 0; while (cond) { __builtin_amdgcn_s_sleep(1); \
;     if ((++_sp & 255u) == 0u) { if (xb_ld(&(bar)[XB_TMO])) break; if (_sp > XB_SPIN_CAP) { atomicAdd(&(bar)[XB_TMO], 1u); break; } } } } while (0)
; __device__ __forceinline__ void xcd_barrier(const XcdBarrier& b, const bool leader) {
;     ...
;     if (leader) {
;         unsigned* bar = b.bar;
;         __builtin_amdgcn_s_waitcnt(0);
;         unsigned nloc = b.st[0], nx = b.st[1];
;         if (nloc == 0u) { xcd_barrier_complete(bar, b.x, nloc, nx); b.st[0] = nloc; b.st[1] = nx; }
;         const unsigned old = xb_add(&bar[XB_XSUB(b.x)], 1u);
;         const unsigned gen = old / nloc;
;         if (old + 1u == (gen + 1u) * nloc) {
;             __builtin_amdgcn_fence(__ATOMIC_RELEASE, "agent");
;             asm volatile("s_waitcnt vmcnt(0)" ::: "memory");
;             const unsigned og = xb_add(&bar[XB_TOP], 1u);
;             const unsigned tg = og / nx;
;             if (og + 1u == (tg + 1u) * nx) xb_add(&bar[XB_TOPGEN], 1u);
;             else XB_SPIN(xb_ld(&bar[XB_TOPGEN]) == tg, bar);
;             __builtin_amdgcn_fence(__ATOMIC_ACQUIRE, "agent");
;             xb_add(&bar[XB_XGEN(b.x)], 1u);
;             asm volatile("s_waitcnt vmcnt(0)" ::: "memory");
;         } else {
;             XB_SPIN(xb_ld(&bar[XB_XGEN(b.x)]) == gen, bar);
;             __builtin_amdgcn_fence(__ATOMIC_ACQUIRE, "agent");
;             asm volatile("s_waitcnt vmcnt(0)" ::: "memory");
;         }
.LBB0_49:
	s_or_b64 exec, exec, s[10:11]
	v_cvt_f32_u32_e32 v6, v4
	s_waitcnt vmcnt(0)
	v_readfirstlane_b32 s1, v5
	v_sub_u32_e32 v5, 0, v4
	v_rcp_iflag_f32_e32 v6, v6
	v_add_u32_e32 v7, s1, v3
	v_mul_f32_e32 v6, 0x4f7ffffe, v6
	v_cvt_u32_f32_e32 v6, v6
	v_mul_lo_u32 v3, v5, v6
	v_mul_hi_u32 v3, v6, v3
	v_add_u32_e32 v3, v6, v3
	v_mul_hi_u32 v3, v7, v3
	v_mul_lo_u32 v5, v3, v4
	v_sub_u32_e32 v5, v7, v5
	v_add_u32_e32 v6, 1, v3
	v_cmp_ge_u32_e32 vcc, v5, v4
	s_nop 1
	v_cndmask_b32_e32 v3, v3, v6, vcc
	v_sub_u32_e32 v6, v5, v4
	v_cndmask_b32_e32 v5, v5, v6, vcc
	v_add_u32_e32 v6, 1, v3
	v_cmp_ge_u32_e32 vcc, v5, v4
	v_add_u32_e32 v5, 1, v7
	s_nop 0
	v_cndmask_b32_e32 v3, v3, v6, vcc
	v_mul_lo_u32 v6, v4, v3
	v_add_u32_e32 v4, v6, v4
	v_add_u32_e32 v6, 1, v6
	v_cmp_eq_u32_e32 vcc, v5, v6
	s_cbranch_vccz .Lewb_0
	buffer_wbl2 sc1
.Lewb_0:
	v_cmp_ne_u32_e32 vcc, v5, v4
	s_and_saveexec_b64 s[2:3], vcc
	s_xor_b64 s[8:9], exec, s[2:3]
	s_cbranch_execz .LBB0_63
	s_waitcnt lgkmcnt(0)
	v_mov_b32_e32 v2, 0x2000
	s_load_dwordx2 s[14:15], s[90:91], 0xb0
	s_waitcnt lgkmcnt(0)
	s_add_u32 s14, s14, 0x1d79b500
	s_addc_u32 s15, s15, 0
	v_mov_b32_e32 v2, 0
	global_load_dword v2, v2, s[14:15] sc1
	s_waitcnt vmcnt(0)
	v_cmp_eq_u32_e32 vcc, v2, v3
	s_and_saveexec_b64 s[10:11], vcc
	s_cbranch_execz .LBB0_62
	s_load_dwordx4 s[16:19], s[90:91], 0xa8
	s_mov_b32 s1, 1
	s_waitcnt lgkmcnt(0)
	s_mov_b64 s[16:17], 0
	v_mov_b32_e32 v2, 0
	s_add_u32 s12, s18, 0x1d798200
	s_addc_u32 s13, s19, 0
	s_branch .LBB0_53

; template <class Epi, class Sched, bool ALIGN_EPI = false, bool SP2 = false>
; __device__ __forceinline__ void gemm_phase(PG8_LAS unsigned char* lds, const Gemm g, const Sched& S, const Epi& E, const int tid_arg) {
;     ...
; #pragma unroll
;         for (int a = 0; a < 2; ++a)
; #pragma unroll
;             for (int b = 0; b < 2; ++b)
; #pragma unroll
;                 for (int m = 0; m < 4; ++m)
; #pragma unroll
;                     for (int n = 0; n < 2; ++n) acc[a][b][m][n] = (f32x4){0.f, 0.f, 0.f, 0.f};
.LBB0_95:
	s_ashr_i32 s21, s20, 31
	s_lshl_b64 s[22:23], s[20:21], 19
	s_add_u32 s22, s1, s22
	s_addc_u32 s23, s2, s23
	s_and_b64 s[24:25], s[6:7], exec
	s_cselect_b32 s21, s23, s29
	s_cselect_b32 s45, s22, s28
	s_ashr_i32 s19, s18, 31
	s_lshl_b64 s[24:25], s[18:19], 19
	s_add_u32 s24, s12, s24
	s_addc_u32 s25, s13, s25
	s_and_b64 s[34:35], s[6:7], exec
	s_cselect_b32 s19, s25, s31
	s_cselect_b32 s46, s24, s30
	s_add_u32 s28, s28, 0x40080
	s_addc_u32 s29, s29, 0
	s_add_u32 s47, s30, 0x100
	v_mov_b32_e32 v2, 0
	s_addc_u32 s48, s31, 0
	s_mov_b32 s49, -2
	v_mov_b32_e32 v3, v2
	v_mov_b32_e32 v4, v2
	v_mov_b32_e32 v5, v2
	v_mov_b32_e32 v6, v2
	v_mov_b32_e32 v7, v2
	v_mov_b32_e32 v8, v2
	v_mov_b32_e32 v9, v2
	v_mov_b32_e32 v18, v2
	v_mov_b32_e32 v19, v2
	v_mov_b32_e32 v20, v2
	v_mov_b32_e32 v21, v2
	v_mov_b32_e32 v22, v2
	v_mov_b32_e32 v23, v2
	v_mov_b32_e32 v24, v2
	v_mov_b32_e32 v25, v2
	v_mov_b32_e32 v34, v2
	v_mov_b32_e32 v35, v2
	v_mov_b32_e32 v36, v2
	v_mov_b32_e32 v37, v2
	v_mov_b32_e32 v38, v2
	v_mov_b32_e32 v39, v2
	v_mov_b32_e32 v40, v2
	v_mov_b32_e32 v41, v2
	v_mov_b32_e32 v50, v2
	v_mov_b32_e32 v51, v2
	v_mov_b32_e32 v52, v2
	v_mov_b32_e32 v53, v2
	v_mov_b32_e32 v54, v2
	v_mov_b32_e32 v55, v2
	v_mov_b32_e32 v56, v2
	v_mov_b32_e32 v57, v2
	v_mov_b32_e32 v10, v2
	v_mov_b32_e32 v11, v2
	v_mov_b32_e32 v12, v2
	v_mov_b32_e32 v13, v2
	v_mov_b32_e32 v14, v2
	v_mov_b32_e32 v15, v2
	v_mov_b32_e32 v16, v2
	v_mov_b32_e32 v17, v2
	v_mov_b32_e32 v26, v2
	v_mov_b32_e32 v27, v2
	v_mov_b32_e32 v28, v2
	v_mov_b32_e32 v29, v2
	v_mov_b32_e32 v30, v2
	v_mov_b32_e32 v31, v2
	v_mov_b32_e32 v32, v2
	v_mov_b32_e32 v33, v2
	v_mov_b32_e32 v42, v2
	v_mov_b32_e32 v43, v2
	v_mov_b32_e32 v44, v2
	v_mov_b32_e32 v45, v2
	v_mov_b32_e32 v46, v2
	v_mov_b32_e32 v47, v2
	v_mov_b32_e32 v48, v2
	v_mov_b32_e32 v49, v2
	v_mov_b32_e32 v58, v2
	v_mov_b32_e32 v59, v2
	v_mov_b32_e32 v60, v2
	v_mov_b32_e32 v61, v2
	v_mov_b32_e32 v62, v2
	v_mov_b32_e32 v63, v2
	v_mov_b32_e32 v64, v2
	v_mov_b32_e32 v65, v2
	v_mov_b32_e32 v66, v2
	v_mov_b32_e32 v67, v2
	v_mov_b32_e32 v68, v2
	v_mov_b32_e32 v69, v2
	v_mov_b32_e32 v70, v2
	v_mov_b32_e32 v71, v2
	v_mov_b32_e32 v72, v2
	v_mov_b32_e32 v73, v2
	v_mov_b32_e32 v82, v2
	v_mov_b32_e32 v83, v2
	v_mov_b32_e32 v84, v2
	v_mov_b32_e32 v85, v2
	v_mov_b32_e32 v86, v2
	v_mov_b32_e32 v87, v2
	v_mov_b32_e32 v88, v2
	v_mov_b32_e32 v89, v2
	v_mov_b32_e32 v98, v2
	v_mov_b32_e32 v99, v2
	v_mov_b32_e32 v100, v2
	v_mov_b32_e32 v101, v2
	v_mov_b32_e32 v102, v2
	v_mov_b32_e32 v103, v2
	v_mov_b32_e32 v104, v2
	v_mov_b32_e32 v105, v2
	v_mov_b32_e32 v114, v2
	v_mov_b32_e32 v115, v2
	v_mov_b32_e32 v116, v2
	v_mov_b32_e32 v117, v2
	v_mov_b32_e32 v118, v2
	v_mov_b32_e32 v119, v2
	v_mov_b32_e32 v120, v2
	v_mov_b32_e32 v121, v2
	v_mov_b32_e32 v74, v2
	v_mov_b32_e32 v75, v2
	v_mov_b32_e32 v76, v2
	v_mov_b32_e32 v77, v2
	v_mov_b32_e32 v78, v2
	v_mov_b32_e32 v79, v2
	v_mov_b32_e32 v80, v2
	v_mov_b32_e32 v81, v2
	v_mov_b32_e32 v90, v2
	v_mov_b32_e32 v91, v2
	v_mov_b32_e32 v92, v2
	v_mov_b32_e32 v93, v2
	v_mov_b32_e32 v94, v2
	v_mov_b32_e32 v95, v2
	v_mov_b32_e32 v96, v2
	v_mov_b32_e32 v97, v2
	v_mov_b32_e32 v106, v2
	v_mov_b32_e32 v107, v2
	v_mov_b32_e32 v108, v2
	v_mov_b32_e32 v109, v2
	v_mov_b32_e32 v110, v2
	v_mov_b32_e32 v111, v2
	v_mov_b32_e32 v112, v2
	v_mov_b32_e32 v113, v2
	v_mov_b32_e32 v122, v2
	v_mov_b32_e32 v123, v2
	v_mov_b32_e32 v124, v2
	v_mov_b32_e32 v125, v2
	v_mov_b32_e32 v126, v2
	v_mov_b32_e32 v127, v2
	v_mov_b32_e32 v128, v2
	v_mov_b32_e32 v129, v2
	s_nop 0
	s_nop 0
	s_nop 0
	s_nop 0
	s_nop 0
	s_nop 0
	s_nop 0
	s_nop 0
	s_nop 0
	s_nop 0
	s_nop 0
	s_nop 0
	s_nop 0
	s_nop 0
	s_nop 0
	s_nop 0
	s_nop 0
	s_nop 0
	s_nop 0

; __device__ __forceinline__ unsigned xb_ld(unsigned* p)              { return __hip_atomic_load(p, __ATOMIC_RELAXED, __HIP_MEMORY_SCOPE_AGENT); }
; #define XB_SPIN(cond, bar) do { unsigned _sp = 0; while (cond) { __builtin_amdgcn_s_sleep(1); \
;     if ((++_sp & 255u) == 0u) { if (xb_ld(&(bar)[XB_TMO])) break; if (_sp > XB_SPIN_CAP) { atomicAdd(&(bar)[XB_TMO], 1u); break; } } } } while (0)
; __device__ __forceinline__ void xcd_barrier(const XcdBarrier& b, const bool leader) {
;     ...
;         } else {
;             XB_SPIN(xb_ld(&bar[XB_XGEN(b.x)]) == gen, bar);
;             __builtin_amdgcn_fence(__ATOMIC_ACQUIRE, "agent");
;             asm volatile("s_waitcnt vmcnt(0)" ::: "memory");
;         }
.Lewb_1:
	v_cmp_ne_u32_e32 vcc, v5, v4
	s_and_saveexec_b64 s[2:3], vcc
	s_xor_b64 s[8:9], exec, s[2:3]
	s_cbranch_execz .LBB0_221
	s_waitcnt lgkmcnt(0)
	v_mov_b32_e32 v2, 0x2000
	s_load_dwordx2 s[16:17], s[90:91], 0xb0
	s_waitcnt lgkmcnt(0)
	s_add_u32 s16, s16, 0x1d79b500
	s_addc_u32 s17, s17, 0
	v_mov_b32_e32 v2, 0
	global_load_dword v2, v2, s[16:17] sc1
	s_waitcnt vmcnt(0)
	v_cmp_eq_u32_e32 vcc, v2, v3
	s_and_saveexec_b64 s[10:11], vcc
	s_cbranch_execz .LBB0_220
	s_add_u32 s14, s12, 0x1d798200
	s_addc_u32 s15, s13, 0
	s_mov_b32 s1, 1
	s_mov_b64 s[18:19], 0
	v_mov_b32_e32 v2, 0
	s_branch .LBB0_211

; #define PG8_STAGE(bufoff, gbase, voff) do { _Pragma("unroll") for (int _i = 0; _i < 2; ++_i) \
;         __builtin_amdgcn_global_load_lds((const unsigned*)((const char*)(gbase) + (voff)[_i]), (PG8_LAS unsigned*)(lds + (bufoff) + ldsw + _i * 8192), 16, 0, 0); } while (0)
; #define PG8_LDA(dst, b, h) do { _Pragma("unroll") for (int m = 0; m < 4; ++m) _Pragma("unroll") for (int k = 0; k < 2; ++k) dst[m][k] = *(const PG8_LAS bf16x8*)(lds + PG8_SA(b, h) + aoff + m * 2048 + k * 1024); } while (0)
; #define PG8_LDB(dst, b, h) do { _Pragma("unroll") for (int n = 0; n < 2; ++n) _Pragma("unroll") for (int k = 0; k < 2; ++k) dst[n][k] = *(const PG8_LAS bf16x8*)(lds + PG8_SB(b, h) + boff + n * 2048 + k * 1024); } while (0)
; #define PG8_MMA(ai, bj, At, Bt) do { __builtin_amdgcn_s_setprio(1); _Pragma("unroll") for (int m = 0; m < 4; ++m) _Pragma("unroll") for (int n = 0; n < 2; ++n) _Pragma("unroll") for (int k = 0; k < 2; ++k) \
;         acc[ai][bj][m][n] = __builtin_amdgcn_mfma_f32_16x16x32_bf16(Bt[n][k], At[m][k], acc[ai][bj][m][n], 0, 0, 0); __builtin_amdgcn_s_setprio(0); } while (0)
; #define PG8_WAIT_V(n) asm volatile("s_waitcnt vmcnt(" #n ")" ::: "memory")
; #define PG8_WAIT_L(n) asm volatile("s_waitcnt lgkmcnt(" #n ")" ::: "memory")
; #define PG8_BAR __builtin_amdgcn_s_barrier()
; #define PG8_SCHED __builtin_amdgcn_sched_barrier(0)
; template <class Epi, class Sched, bool ALIGN_EPI = false, bool SP2 = false>
; __device__ __forceinline__ void gemm_phase(PG8_LAS unsigned char* lds, const Gemm g, const Sched& S, const Epi& E, const int tid_arg) {
;     ...
;         for (int t = 0; t < nt; t += 2) {
;             const bool last = (t == nt - 2);
;             const char* a1 = cA + (size_t)(t + 1) * kstep;
;             const char* a2 = last ? nA : cA + (size_t)(t + 2) * kstep; const char* b2 = last ? nB : cB + (size_t)(t + 2) * kstep;
;             const char* a3 = a2 + kstep; const char* b3 = b2 + kstep;
;             if (last && has_next) S.a_ready(nxt);
;             if constexpr (SP2) {
;             PG8_LDB(B0, 0, 0); PG8_LDB(B1, 0, 1); PG8_SCHED; PG8_LDA(At, 0, 0); PG8_STAGE(PG8_SA(1, 1), a1 + hstep, voffA);
;             PG8_WAIT_V(8); PG8_WAIT_L(0); PG8_BAR; PG8_MMA(0, 0, At, B0); PG8_MMA(0, 1, At, B1); PG8_BAR; PG8_SCHED;
.LBB0_259:
	s_add_u32 s16, s36, 0x100
	v_mov_b32_e32 v2, 0
	s_addc_u32 s31, s37, 0
	s_mov_b32 s56, -2
	s_waitcnt lgkmcnt(0)
	v_mov_b32_e32 v3, v2
	v_mov_b32_e32 v4, v2
	v_mov_b32_e32 v5, v2
	v_mov_b32_e32 v6, v2
	v_mov_b32_e32 v7, v2
	v_mov_b32_e32 v8, v2
	v_mov_b32_e32 v9, v2
	v_mov_b32_e32 v18, v2
	v_mov_b32_e32 v19, v2
	v_mov_b32_e32 v20, v2
	v_mov_b32_e32 v21, v2
	v_mov_b32_e32 v22, v2
	v_mov_b32_e32 v23, v2
	v_mov_b32_e32 v24, v2
	v_mov_b32_e32 v25, v2
	v_mov_b32_e32 v34, v2
	v_mov_b32_e32 v35, v2
	v_mov_b32_e32 v36, v2
	v_mov_b32_e32 v37, v2
	v_mov_b32_e32 v38, v2
	v_mov_b32_e32 v39, v2
	v_mov_b32_e32 v40, v2
	v_mov_b32_e32 v41, v2
	v_mov_b32_e32 v50, v2
	v_mov_b32_e32 v51, v2
	v_mov_b32_e32 v52, v2
	v_mov_b32_e32 v53, v2
	v_mov_b32_e32 v54, v2
	v_mov_b32_e32 v55, v2
	v_mov_b32_e32 v56, v2
	v_mov_b32_e32 v57, v2
	v_mov_b32_e32 v10, v2
	v_mov_b32_e32 v11, v2
	v_mov_b32_e32 v12, v2
	v_mov_b32_e32 v13, v2
	v_mov_b32_e32 v14, v2
	v_mov_b32_e32 v15, v2
	v_mov_b32_e32 v16, v2
	v_mov_b32_e32 v17, v2
	v_mov_b32_e32 v26, v2
	v_mov_b32_e32 v27, v2
	v_mov_b32_e32 v28, v2
	v_mov_b32_e32 v29, v2
	v_mov_b32_e32 v30, v2
	v_mov_b32_e32 v31, v2
	v_mov_b32_e32 v32, v2
	v_mov_b32_e32 v33, v2
	v_mov_b32_e32 v42, v2
	v_mov_b32_e32 v43, v2
	v_mov_b32_e32 v44, v2
	v_mov_b32_e32 v45, v2
	v_mov_b32_e32 v46, v2
	v_mov_b32_e32 v47, v2
	v_mov_b32_e32 v48, v2
	v_mov_b32_e32 v49, v2
	v_mov_b32_e32 v58, v2
	v_mov_b32_e32 v59, v2
	v_mov_b32_e32 v60, v2
	v_mov_b32_e32 v61, v2
	v_mov_b32_e32 v62, v2
	v_mov_b32_e32 v63, v2
	v_mov_b32_e32 v64, v2
	v_mov_b32_e32 v65, v2
	v_mov_b32_e32 v66, v2
	v_mov_b32_e32 v67, v2
	v_mov_b32_e32 v68, v2
	v_mov_b32_e32 v69, v2
	v_mov_b32_e32 v70, v2
	v_mov_b32_e32 v71, v2
	v_mov_b32_e32 v72, v2
	v_mov_b32_e32 v73, v2
	v_mov_b32_e32 v82, v2
	v_mov_b32_e32 v83, v2
	v_mov_b32_e32 v84, v2
	v_mov_b32_e32 v85, v2
	v_mov_b32_e32 v86, v2
	v_mov_b32_e32 v87, v2
	v_mov_b32_e32 v88, v2
	v_mov_b32_e32 v89, v2
	v_mov_b32_e32 v98, v2
	v_mov_b32_e32 v99, v2
	v_mov_b32_e32 v100, v2
	v_mov_b32_e32 v101, v2
	v_mov_b32_e32 v102, v2
	v_mov_b32_e32 v103, v2
	v_mov_b32_e32 v104, v2
	v_mov_b32_e32 v105, v2
	v_mov_b32_e32 v114, v2
	v_mov_b32_e32 v115, v2
	v_mov_b32_e32 v116, v2
	v_mov_b32_e32 v117, v2
	v_mov_b32_e32 v118, v2
	v_mov_b32_e32 v119, v2
	v_mov_b32_e32 v120, v2
	v_mov_b32_e32 v121, v2
	v_mov_b32_e32 v74, v2
	v_mov_b32_e32 v75, v2
	v_mov_b32_e32 v76, v2
	v_mov_b32_e32 v77, v2
	v_mov_b32_e32 v78, v2
	v_mov_b32_e32 v79, v2
	v_mov_b32_e32 v80, v2
	v_mov_b32_e32 v81, v2
	v_mov_b32_e32 v90, v2
	v_mov_b32_e32 v91, v2
	v_mov_b32_e32 v92, v2
	v_mov_b32_e32 v93, v2
	v_mov_b32_e32 v94, v2
	v_mov_b32_e32 v95, v2
	v_mov_b32_e32 v96, v2
	v_mov_b32_e32 v97, v2
	v_mov_b32_e32 v106, v2
	v_mov_b32_e32 v107, v2
	v_mov_b32_e32 v108, v2
	v_mov_b32_e32 v109, v2
	v_mov_b32_e32 v110, v2
	v_mov_b32_e32 v111, v2
	v_mov_b32_e32 v112, v2
	v_mov_b32_e32 v113, v2
	v_mov_b32_e32 v122, v2
	v_mov_b32_e32 v123, v2
	v_mov_b32_e32 v124, v2
	v_mov_b32_e32 v125, v2
	v_mov_b32_e32 v126, v2
	v_mov_b32_e32 v127, v2
	v_mov_b32_e32 v128, v2
	v_mov_b32_e32 v129, v2
	s_nop 0
	s_nop 0
	s_nop 0
	s_nop 0
	s_nop 0
	s_nop 0
	s_nop 0
	s_nop 0
	s_nop 0
	s_nop 0
	s_nop 0
	s_nop 0
	s_nop 0
.LBB0_260:
	ds_read_b128 v[146:149], v162
	ds_read_b128 v[166:169], v162 offset:1024
	ds_read_b128 v[170:173], v162 offset:2048
	ds_read_b128 v[174:177], v162 offset:3072
	ds_read_b128 v[182:185], v163
	ds_read_b128 v[186:189], v163 offset:1024
	ds_read_b128 v[190:193], v163 offset:2048
	ds_read_b128 v[202:205], v163 offset:3072
	s_add_u32 s36, s34, 0x100
	s_addc_u32 s37, s35, 0
	s_cmp_eq_u32 s56, 40
	s_cselect_b32 s41, s13, s37
	s_cselect_b32 s40, s12, s36
	s_cselect_b32 s39, s29, s31
	s_cselect_b32 s38, s28, s16
	v_lshl_add_u64 v[150:151], s[34:35], 0, v[138:139]
	s_add_i32 m0, s43, 0xc000
	ds_read_b128 v[206:209], v164
	ds_read_b128 v[210:213], v164 offset:1024
	ds_read_b128 v[214:217], v164 offset:2048
	ds_read_b128 v[218:221], v164 offset:3072
	ds_read_b128 v[222:225], v164 offset:4096
	ds_read_b128 v[226:229], v164 offset:5120
	ds_read_b128 v[230:233], v164 offset:6144
	ds_read_b128 v[234:237], v164 offset:7168
	global_load_lds_dwordx4 v[150:151], off
	v_lshl_add_u64 v[150:151], s[34:35], 0, v[140:141]
	s_add_i32 m0, s43, 0xe000
	s_nop 0
	global_load_lds_dwordx4 v[150:151], off
	s_waitcnt vmcnt(8)
	s_waitcnt lgkmcnt(0)
	s_barrier
	s_setprio 1
	s_waitcnt lgkmcnt(0)
	v_mfma_f32_16x16x32_bf16 v[126:129], v[146:149], v[206:209], v[126:129]
	v_mfma_f32_16x16x32_bf16 v[122:125], v[170:173], v[206:209], v[122:125]
	v_mfma_f32_16x16x32_bf16 v[110:113], v[146:149], v[214:217], v[110:113]
	v_mfma_f32_16x16x32_bf16 v[106:109], v[170:173], v[214:217], v[106:109]
	v_mfma_f32_16x16x32_bf16 v[94:97], v[146:149], v[222:225], v[94:97]
	v_mfma_f32_16x16x32_bf16 v[90:93], v[170:173], v[222:225], v[90:93]
	v_mfma_f32_16x16x32_bf16 v[78:81], v[146:149], v[230:233], v[78:81]
	v_mfma_f32_16x16x32_bf16 v[74:77], v[170:173], v[230:233], v[74:77]
	v_mfma_f32_16x16x32_bf16 v[126:129], v[166:169], v[210:213], v[126:129]
	v_mfma_f32_16x16x32_bf16 v[122:125], v[174:177], v[210:213], v[122:125]
	v_mfma_f32_16x16x32_bf16 v[110:113], v[166:169], v[218:221], v[110:113]
	v_mfma_f32_16x16x32_bf16 v[106:109], v[174:177], v[218:221], v[106:109]
	v_mfma_f32_16x16x32_bf16 v[94:97], v[166:169], v[226:229], v[94:97]
	v_mfma_f32_16x16x32_bf16 v[90:93], v[174:177], v[226:229], v[90:93]
	v_mfma_f32_16x16x32_bf16 v[78:81], v[166:169], v[234:237], v[78:81]
	v_mfma_f32_16x16x32_bf16 v[74:77], v[174:177], v[234:237], v[74:77]
	s_setprio 0
	s_setprio 1
	v_mfma_f32_16x16x32_bf16 v[118:121], v[182:185], v[206:209], v[118:121]
	v_mfma_f32_16x16x32_bf16 v[114:117], v[190:193], v[206:209], v[114:117]
	v_mfma_f32_16x16x32_bf16 v[102:105], v[182:185], v[214:217], v[102:105]
	v_mfma_f32_16x16x32_bf16 v[98:101], v[190:193], v[214:217], v[98:101]
	v_mfma_f32_16x16x32_bf16 v[86:89], v[182:185], v[222:225], v[86:89]
	v_mfma_f32_16x16x32_bf16 v[82:85], v[190:193], v[222:225], v[82:85]
	v_mfma_f32_16x16x32_bf16 v[70:73], v[182:185], v[230:233], v[70:73]
	v_mfma_f32_16x16x32_bf16 v[66:69], v[190:193], v[230:233], v[66:69]
	v_mfma_f32_16x16x32_bf16 v[118:121], v[186:189], v[210:213], v[118:121]
	v_mfma_f32_16x16x32_bf16 v[114:117], v[202:205], v[210:213], v[114:117]
	v_mfma_f32_16x16x32_bf16 v[102:105], v[186:189], v[218:221], v[102:105]
	v_mfma_f32_16x16x32_bf16 v[98:101], v[202:205], v[218:221], v[98:101]
	v_mfma_f32_16x16x32_bf16 v[86:89], v[186:189], v[226:229], v[86:89]
	v_mfma_f32_16x16x32_bf16 v[82:85], v[202:205], v[226:229], v[82:85]
	v_mfma_f32_16x16x32_bf16 v[70:73], v[186:189], v[234:237], v[70:73]
	v_mfma_f32_16x16x32_bf16 v[66:69], v[202:205], v[234:237], v[66:69]
	s_setprio 0
	s_barrier
; #define PG8_STAGE(bufoff, gbase, voff) do { _Pragma("unroll") for (int _i = 0; _i < 2; ++_i) \
;         __builtin_amdgcn_global_load_lds((const unsigned*)((const char*)(gbase) + (voff)[_i]), (PG8_LAS unsigned*)(lds + (bufoff) + ldsw + _i * 8192), 16, 0, 0); } while (0)
; #define PG8_LDA(dst, b, h) do { _Pragma("unroll") for (int m = 0; m < 4; ++m) _Pragma("unroll") for (int k = 0; k < 2; ++k) dst[m][k] = *(const PG8_LAS bf16x8*)(lds + PG8_SA(b, h) + aoff + m * 2048 + k * 1024); } while (0)
; #define PG8_LDB(dst, b, h) do { _Pragma("unroll") for (int n = 0; n < 2; ++n) _Pragma("unroll") for (int k = 0; k < 2; ++k) dst[n][k] = *(const PG8_LAS bf16x8*)(lds + PG8_SB(b, h) + boff + n * 2048 + k * 1024); } while (0)
; #define PG8_MMA(ai, bj, At, Bt) do { __builtin_amdgcn_s_setprio(1); _Pragma("unroll") for (int m = 0; m < 4; ++m) _Pragma("unroll") for (int n = 0; n < 2; ++n) _Pragma("unroll") for (int k = 0; k < 2; ++k) \
;         acc[ai][bj][m][n] = __builtin_amdgcn_mfma_f32_16x16x32_bf16(Bt[n][k], At[m][k], acc[ai][bj][m][n], 0, 0, 0); __builtin_amdgcn_s_setprio(0); } while (0)
; #define PG8_WAIT_V(n) asm volatile("s_waitcnt vmcnt(" #n ")" ::: "memory")
; #define PG8_WAIT_L(n) asm volatile("s_waitcnt lgkmcnt(" #n ")" ::: "memory")
; #define PG8_BAR __builtin_amdgcn_s_barrier()
; #define PG8_SCHED __builtin_amdgcn_sched_barrier(0)
; template <class Epi, class Sched, bool ALIGN_EPI = false, bool SP2 = false>
; __device__ __forceinline__ void gemm_phase(PG8_LAS unsigned char* lds, const Gemm g, const Sched& S, const Epi& E, const int tid_arg) {
;     ...
;             PG8_WAIT_V(8); PG8_WAIT_L(0); PG8_BAR; PG8_MMA(0, 0, At, B0); PG8_MMA(0, 1, At, B1); PG8_BAR; PG8_SCHED;
;             PG8_LDA(At, 0, 1); PG8_STAGE(PG8_SB(0, 0), b2, voffB); PG8_STAGE(PG8_SB(0, 1), b2 + hstep, voffB); PG8_STAGE(PG8_SA(0, 0), a2, voffA);
;             PG8_WAIT_V(8); PG8_WAIT_L(0); PG8_BAR; PG8_MMA(1, 0, At, B0); PG8_MMA(1, 1, At, B1); PG8_BAR; PG8_SCHED;
;             PG8_LDB(B0, 1, 0); PG8_LDB(B1, 1, 1); PG8_SCHED; PG8_LDA(At, 1, 0); PG8_STAGE(PG8_SA(0, 1), a2 + hstep, voffA);
;             PG8_WAIT_V(8); PG8_WAIT_L(0); PG8_BAR; PG8_MMA(0, 0, At, B0); PG8_MMA(0, 1, At, B1); PG8_BAR; PG8_SCHED;
	s_add_i32 s34, s50, s42
	v_lshl_add_u64 v[150:151], s[38:39], 0, v[132:133]
	s_mov_b32 m0, s34
	ds_read_b128 v[206:209], v164 offset:16384
	ds_read_b128 v[210:213], v164 offset:17408
	ds_read_b128 v[214:217], v164 offset:18432
	ds_read_b128 v[218:221], v164 offset:19456
	ds_read_b128 v[222:225], v164 offset:20480
	ds_read_b128 v[226:229], v164 offset:21504
	ds_read_b128 v[230:233], v164 offset:22528
	ds_read_b128 v[234:237], v164 offset:23552
	global_load_lds_dwordx4 v[150:151], off
	s_add_i32 m0, s34, 0x2000
	s_add_u32 s34, s38, 0xb0000
	v_lshl_add_u64 v[178:179], s[38:39], 0, v[136:137]
	s_addc_u32 s35, s39, 0
	s_add_i32 s57, s51, s42
	global_load_lds_dwordx4 v[178:179], off
	v_lshl_add_u64 v[194:195], s[34:35], 0, v[132:133]
	s_mov_b32 m0, s57
	v_lshl_add_u64 v[238:239], s[40:41], 0, v[134:135]
	global_load_lds_dwordx4 v[194:195], off
	v_lshl_add_u64 v[194:195], s[34:35], 0, v[136:137]
	s_add_i32 m0, s57, 0x2000
	s_nop 0
	global_load_lds_dwordx4 v[194:195], off
	v_lshl_add_u64 v[194:195], s[40:41], 0, v[130:131]
	s_mov_b32 m0, s43
	s_nop 0
	global_load_lds_dwordx4 v[194:195], off
	s_mov_b32 m0, s44
	s_nop 0
	global_load_lds_dwordx4 v[238:239], off
	s_waitcnt vmcnt(8)
	s_waitcnt lgkmcnt(0)
	s_barrier
	s_setprio 1
	s_waitcnt lgkmcnt(0)
	v_mfma_f32_16x16x32_bf16 v[62:65], v[146:149], v[206:209], v[62:65]
	v_mfma_f32_16x16x32_bf16 v[58:61], v[170:173], v[206:209], v[58:61]
	v_mfma_f32_16x16x32_bf16 v[46:49], v[146:149], v[214:217], v[46:49]
	v_mfma_f32_16x16x32_bf16 v[42:45], v[170:173], v[214:217], v[42:45]
	v_mfma_f32_16x16x32_bf16 v[30:33], v[146:149], v[222:225], v[30:33]
	v_mfma_f32_16x16x32_bf16 v[26:29], v[170:173], v[222:225], v[26:29]
	v_mfma_f32_16x16x32_bf16 v[14:17], v[146:149], v[230:233], v[14:17]
	v_mfma_f32_16x16x32_bf16 v[10:13], v[170:173], v[230:233], v[10:13]
	v_mfma_f32_16x16x32_bf16 v[62:65], v[166:169], v[210:213], v[62:65]
	v_mfma_f32_16x16x32_bf16 v[58:61], v[174:177], v[210:213], v[58:61]
	v_mfma_f32_16x16x32_bf16 v[46:49], v[166:169], v[218:221], v[46:49]
	v_mfma_f32_16x16x32_bf16 v[42:45], v[174:177], v[218:221], v[42:45]
	v_mfma_f32_16x16x32_bf16 v[30:33], v[166:169], v[226:229], v[30:33]
	v_mfma_f32_16x16x32_bf16 v[26:29], v[174:177], v[226:229], v[26:29]
	v_mfma_f32_16x16x32_bf16 v[14:17], v[166:169], v[234:237], v[14:17]
	v_mfma_f32_16x16x32_bf16 v[10:13], v[174:177], v[234:237], v[10:13]
	s_setprio 0
	s_setprio 1
	v_mfma_f32_16x16x32_bf16 v[54:57], v[182:185], v[206:209], v[54:57]
	v_mfma_f32_16x16x32_bf16 v[50:53], v[190:193], v[206:209], v[50:53]
	v_mfma_f32_16x16x32_bf16 v[38:41], v[182:185], v[214:217], v[38:41]
	v_mfma_f32_16x16x32_bf16 v[34:37], v[190:193], v[214:217], v[34:37]
	v_mfma_f32_16x16x32_bf16 v[22:25], v[182:185], v[222:225], v[22:25]
	v_mfma_f32_16x16x32_bf16 v[18:21], v[190:193], v[222:225], v[18:21]
	v_mfma_f32_16x16x32_bf16 v[6:9], v[182:185], v[230:233], v[6:9]
	v_mfma_f32_16x16x32_bf16 v[2:5], v[190:193], v[230:233], v[2:5]
	v_mfma_f32_16x16x32_bf16 v[54:57], v[186:189], v[210:213], v[54:57]
	v_mfma_f32_16x16x32_bf16 v[50:53], v[202:205], v[210:213], v[50:53]
	v_mfma_f32_16x16x32_bf16 v[38:41], v[186:189], v[218:221], v[38:41]
	v_mfma_f32_16x16x32_bf16 v[34:37], v[202:205], v[218:221], v[34:37]
	v_mfma_f32_16x16x32_bf16 v[22:25], v[186:189], v[226:229], v[22:25]
	v_mfma_f32_16x16x32_bf16 v[18:21], v[202:205], v[226:229], v[18:21]
	v_mfma_f32_16x16x32_bf16 v[6:9], v[186:189], v[234:237], v[6:9]
	v_mfma_f32_16x16x32_bf16 v[2:5], v[202:205], v[234:237], v[2:5]
	s_setprio 0
	s_barrier
	s_add_i32 s57, 0, 0x18000
	v_add_u32_e32 v165, s57, v153
	s_add_i32 s58, 0, 0x1c000
	ds_read_b128 v[146:149], v165
	ds_read_b128 v[166:169], v165 offset:1024
	ds_read_b128 v[170:173], v165 offset:2048
	ds_read_b128 v[174:177], v165 offset:3072
	v_add_u32_e32 v165, s58, v153
	ds_read_b128 v[182:185], v165
	ds_read_b128 v[186:189], v165 offset:1024
	ds_read_b128 v[190:193], v165 offset:2048
	ds_read_b128 v[202:205], v165 offset:3072
	s_add_u32 s34, s40, 0xb0000
	s_addc_u32 s35, s41, 0
	s_mov_b32 m0, s45
	v_lshl_add_u64 v[240:241], s[34:35], 0, v[130:131]
	ds_read_b128 v[206:209], v164 offset:32768
	ds_read_b128 v[210:213], v164 offset:33792
	ds_read_b128 v[214:217], v164 offset:34816
	ds_read_b128 v[218:221], v164 offset:35840
	ds_read_b128 v[222:225], v164 offset:36864
	ds_read_b128 v[226:229], v164 offset:37888
	ds_read_b128 v[230:233], v164 offset:38912
	ds_read_b128 v[234:237], v164 offset:39936
	global_load_lds_dwordx4 v[240:241], off
	v_lshl_add_u64 v[240:241], s[34:35], 0, v[134:135]
	s_mov_b32 m0, s46
	s_nop 0
	global_load_lds_dwordx4 v[240:241], off
	s_waitcnt vmcnt(8)
	s_waitcnt lgkmcnt(0)
	s_barrier
; #define PG8_STAGE(bufoff, gbase, voff) do { _Pragma("unroll") for (int _i = 0; _i < 2; ++_i) \
;         __builtin_amdgcn_global_load_lds((const unsigned*)((const char*)(gbase) + (voff)[_i]), (PG8_LAS unsigned*)(lds + (bufoff) + ldsw + _i * 8192), 16, 0, 0); } while (0)
; #define PG8_WAIT_V(n) asm volatile("s_waitcnt vmcnt(" #n ")" ::: "memory")
; template <class Epi, class Sched, bool ALIGN_EPI = false, bool SP2 = false>
; __device__ __forceinline__ void gemm_phase(PG8_LAS unsigned char* lds, const Gemm g, const Sched& S, const Epi& E, const int tid_arg) {
;     ...
;             PG8_WAIT_V(8); PG8_WAIT_L(0); PG8_BAR; PG8_MMA(0, 0, At, B0); PG8_MMA(0, 1, At, B1); PG8_BAR; PG8_SCHED;
;             PG8_LDA(At, 1, 1); PG8_STAGE(PG8_SB(1, 0), b3, voffB); PG8_STAGE(PG8_SB(1, 1), b3 + hstep, voffB); PG8_STAGE(PG8_SA(1, 0), a3, voffA);
;             PG8_WAIT_V(8); PG8_WAIT_L(0); PG8_BAR; PG8_MMA(1, 0, At, B0); PG8_MMA(1, 1, At, B1); PG8_BAR; PG8_SCHED;
;             } else {
;             PG8_LDB(B0, 0, 0); PG8_SCHED; PG8_LDA(At, 0, 0); PG8_STAGE(PG8_SA(1, 1), a1 + hstep, voffA);
;             PG8_WAIT_L(8); PG8_BAR; PG8_WAIT_L(0); PG8_MMA(0, 0, At, B0); PG8_BAR; PG8_SCHED;
;             PG8_LDB(B1, 0, 1); PG8_STAGE(PG8_SB(0, 0), b2, voffB);
;             PG8_BAR; PG8_WAIT_L(0); PG8_MMA(0, 1, At, B1); PG8_BAR;
;             PG8_LDA(At, 0, 1); PG8_STAGE(PG8_SA(0, 0), a2, voffA);
;             PG8_BAR; PG8_WAIT_L(0); PG8_MMA(1, 0, At, B0); PG8_BAR; PG8_SCHED;
;             PG8_STAGE(PG8_SB(0, 1), b2 + hstep, voffB);
;             PG8_WAIT_V(6); PG8_BAR; PG8_MMA(1, 1, At, B1); PG8_BAR;
;             PG8_LDB(B0, 1, 0); PG8_SCHED; PG8_LDA(At, 1, 0); PG8_STAGE(PG8_SA(0, 1), a2 + hstep, voffA);
;             PG8_WAIT_L(8); PG8_BAR; PG8_WAIT_L(0); PG8_MMA(0, 0, At, B0); PG8_BAR; PG8_SCHED;
;             PG8_LDB(B1, 1, 1); PG8_STAGE(PG8_SB(1, 0), b3, voffB);
;             PG8_BAR; PG8_WAIT_L(0); PG8_MMA(0, 1, At, B1); PG8_BAR;
;             PG8_LDA(At, 1, 1); PG8_STAGE(PG8_SA(1, 0), a3, voffA);
;             PG8_BAR; PG8_WAIT_L(0); PG8_MMA(1, 0, At, B0); PG8_BAR; PG8_SCHED;
;             PG8_STAGE(PG8_SB(1, 1), b3 + hstep, voffB);
;             PG8_WAIT_V(6); PG8_BAR; PG8_MMA(1, 1, At, B1); PG8_BAR;
;             }
;         }
;         if constexpr (ALIGN_EPI) { if (wr == 0) PG8_BAR; }
;         if constexpr (!Epi::AFTER_DRAIN) { E(acc, cur, wr, wc, fr, fq); S.done(cur); }
	s_setprio 1
	s_waitcnt lgkmcnt(0)
	v_mfma_f32_16x16x32_bf16 v[126:129], v[146:149], v[206:209], v[126:129]
	v_mfma_f32_16x16x32_bf16 v[122:125], v[170:173], v[206:209], v[122:125]
	v_mfma_f32_16x16x32_bf16 v[110:113], v[146:149], v[214:217], v[110:113]
	v_mfma_f32_16x16x32_bf16 v[106:109], v[170:173], v[214:217], v[106:109]
	v_mfma_f32_16x16x32_bf16 v[94:97], v[146:149], v[222:225], v[94:97]
	v_mfma_f32_16x16x32_bf16 v[90:93], v[170:173], v[222:225], v[90:93]
	v_mfma_f32_16x16x32_bf16 v[78:81], v[146:149], v[230:233], v[78:81]
	v_mfma_f32_16x16x32_bf16 v[74:77], v[170:173], v[230:233], v[74:77]
	v_mfma_f32_16x16x32_bf16 v[126:129], v[166:169], v[210:213], v[126:129]
	v_mfma_f32_16x16x32_bf16 v[122:125], v[174:177], v[210:213], v[122:125]
	v_mfma_f32_16x16x32_bf16 v[110:113], v[166:169], v[218:221], v[110:113]
	v_mfma_f32_16x16x32_bf16 v[106:109], v[174:177], v[218:221], v[106:109]
	v_mfma_f32_16x16x32_bf16 v[94:97], v[166:169], v[226:229], v[94:97]
	v_mfma_f32_16x16x32_bf16 v[90:93], v[174:177], v[226:229], v[90:93]
	v_mfma_f32_16x16x32_bf16 v[78:81], v[166:169], v[234:237], v[78:81]
	v_mfma_f32_16x16x32_bf16 v[74:77], v[174:177], v[234:237], v[74:77]
	s_setprio 0
	s_setprio 1
	v_mfma_f32_16x16x32_bf16 v[118:121], v[182:185], v[206:209], v[118:121]
	v_mfma_f32_16x16x32_bf16 v[114:117], v[190:193], v[206:209], v[114:117]
	v_mfma_f32_16x16x32_bf16 v[102:105], v[182:185], v[214:217], v[102:105]
	v_mfma_f32_16x16x32_bf16 v[98:101], v[190:193], v[214:217], v[98:101]
	v_mfma_f32_16x16x32_bf16 v[86:89], v[182:185], v[222:225], v[86:89]
	v_mfma_f32_16x16x32_bf16 v[82:85], v[190:193], v[222:225], v[82:85]
	v_mfma_f32_16x16x32_bf16 v[70:73], v[182:185], v[230:233], v[70:73]
	v_mfma_f32_16x16x32_bf16 v[66:69], v[190:193], v[230:233], v[66:69]
	v_mfma_f32_16x16x32_bf16 v[118:121], v[186:189], v[210:213], v[118:121]
	v_mfma_f32_16x16x32_bf16 v[114:117], v[202:205], v[210:213], v[114:117]
	v_mfma_f32_16x16x32_bf16 v[102:105], v[186:189], v[218:221], v[102:105]
	v_mfma_f32_16x16x32_bf16 v[98:101], v[202:205], v[218:221], v[98:101]
	v_mfma_f32_16x16x32_bf16 v[86:89], v[186:189], v[226:229], v[86:89]
	v_mfma_f32_16x16x32_bf16 v[82:85], v[202:205], v[226:229], v[82:85]
	v_mfma_f32_16x16x32_bf16 v[70:73], v[186:189], v[234:237], v[70:73]
	v_mfma_f32_16x16x32_bf16 v[66:69], v[202:205], v[234:237], v[66:69]
	s_setprio 0
	s_barrier
	s_add_i32 s34, s57, s42
	v_lshl_add_u64 v[150:151], v[150:151], 0, s[24:25]
	s_mov_b32 m0, s34
	ds_read_b128 v[206:209], v164 offset:49152
	ds_read_b128 v[210:213], v164 offset:50176
	ds_read_b128 v[214:217], v164 offset:51200
	ds_read_b128 v[218:221], v164 offset:52224
	ds_read_b128 v[222:225], v164 offset:53248
	ds_read_b128 v[226:229], v164 offset:54272
	ds_read_b128 v[230:233], v164 offset:55296
	ds_read_b128 v[234:237], v164 offset:56320
	global_load_lds_dwordx4 v[150:151], off
	s_add_i32 m0, s34, 0x2000
	s_add_u32 s34, s38, 0xb0080
	v_lshl_add_u64 v[150:151], v[178:179], 0, s[24:25]
	s_addc_u32 s35, s39, 0
	s_add_i32 s38, s58, s42
	global_load_lds_dwordx4 v[150:151], off
	v_lshl_add_u64 v[150:151], s[34:35], 0, v[132:133]
	s_mov_b32 m0, s38
	s_nop 0
	global_load_lds_dwordx4 v[150:151], off
	v_lshl_add_u64 v[150:151], s[34:35], 0, v[136:137]
	s_add_i32 m0, s38, 0x2000
	s_nop 0
	global_load_lds_dwordx4 v[150:151], off
	v_lshl_add_u64 v[150:151], v[194:195], 0, s[24:25]
	s_mov_b32 m0, s48
	s_nop 0
	global_load_lds_dwordx4 v[150:151], off
	v_lshl_add_u64 v[150:151], v[238:239], 0, s[24:25]
	s_mov_b32 m0, s49
	s_nop 0
	global_load_lds_dwordx4 v[150:151], off
	s_waitcnt vmcnt(8)
	s_waitcnt lgkmcnt(0)
	s_barrier
	s_setprio 1
	s_waitcnt lgkmcnt(0)
	v_mfma_f32_16x16x32_bf16 v[62:65], v[146:149], v[206:209], v[62:65]
	v_mfma_f32_16x16x32_bf16 v[58:61], v[170:173], v[206:209], v[58:61]
	v_mfma_f32_16x16x32_bf16 v[46:49], v[146:149], v[214:217], v[46:49]
	v_mfma_f32_16x16x32_bf16 v[42:45], v[170:173], v[214:217], v[42:45]
	v_mfma_f32_16x16x32_bf16 v[30:33], v[146:149], v[222:225], v[30:33]
	v_mfma_f32_16x16x32_bf16 v[26:29], v[170:173], v[222:225], v[26:29]
	v_mfma_f32_16x16x32_bf16 v[14:17], v[146:149], v[230:233], v[14:17]
	v_mfma_f32_16x16x32_bf16 v[10:13], v[170:173], v[230:233], v[10:13]
	v_mfma_f32_16x16x32_bf16 v[62:65], v[166:169], v[210:213], v[62:65]
	v_mfma_f32_16x16x32_bf16 v[58:61], v[174:177], v[210:213], v[58:61]
	v_mfma_f32_16x16x32_bf16 v[46:49], v[166:169], v[218:221], v[46:49]
	v_mfma_f32_16x16x32_bf16 v[42:45], v[174:177], v[218:221], v[42:45]
	v_mfma_f32_16x16x32_bf16 v[30:33], v[166:169], v[226:229], v[30:33]
	v_mfma_f32_16x16x32_bf16 v[26:29], v[174:177], v[226:229], v[26:29]
	v_mfma_f32_16x16x32_bf16 v[14:17], v[166:169], v[234:237], v[14:17]
	v_mfma_f32_16x16x32_bf16 v[10:13], v[174:177], v[234:237], v[10:13]
	s_setprio 0
	s_setprio 1
	v_mfma_f32_16x16x32_bf16 v[54:57], v[182:185], v[206:209], v[54:57]
	v_mfma_f32_16x16x32_bf16 v[50:53], v[190:193], v[206:209], v[50:53]
	v_mfma_f32_16x16x32_bf16 v[38:41], v[182:185], v[214:217], v[38:41]
	v_mfma_f32_16x16x32_bf16 v[34:37], v[190:193], v[214:217], v[34:37]
	v_mfma_f32_16x16x32_bf16 v[22:25], v[182:185], v[222:225], v[22:25]
	v_mfma_f32_16x16x32_bf16 v[18:21], v[190:193], v[222:225], v[18:21]
	v_mfma_f32_16x16x32_bf16 v[6:9], v[182:185], v[230:233], v[6:9]
	v_mfma_f32_16x16x32_bf16 v[2:5], v[190:193], v[230:233], v[2:5]
	v_mfma_f32_16x16x32_bf16 v[54:57], v[186:189], v[210:213], v[54:57]
	v_mfma_f32_16x16x32_bf16 v[50:53], v[202:205], v[210:213], v[50:53]
	v_mfma_f32_16x16x32_bf16 v[38:41], v[186:189], v[218:221], v[38:41]
	v_mfma_f32_16x16x32_bf16 v[34:37], v[202:205], v[218:221], v[34:37]
	v_mfma_f32_16x16x32_bf16 v[22:25], v[186:189], v[226:229], v[22:25]
	v_mfma_f32_16x16x32_bf16 v[18:21], v[202:205], v[226:229], v[18:21]
	v_mfma_f32_16x16x32_bf16 v[6:9], v[186:189], v[234:237], v[6:9]
	v_mfma_f32_16x16x32_bf16 v[2:5], v[202:205], v[234:237], v[2:5]
	s_setprio 0
	s_barrier
	s_add_i32 s56, s56, 2
	s_add_u32 s16, s16, 0x100
	s_addc_u32 s31, s31, 0
	s_cmp_gt_u32 s56, 41
	s_mov_b64 s[34:35], s[36:37]
	s_cbranch_scc0 .LBB0_260
	s_and_b64 vcc, exec, s[26:27]
	s_cbranch_vccz .LBB0_284
	s_barrier
	s_cmpk_gt_i32 s30, 0x7f
	s_mov_b64 s[36:37], -1
	s_cbranch_scc1 .LBB0_285

; __device__ __forceinline__ unsigned xb_ld(unsigned* p)              { return __hip_atomic_load(p, __ATOMIC_RELAXED, __HIP_MEMORY_SCOPE_AGENT); }
; __device__ __forceinline__ unsigned xb_add(unsigned* p, unsigned v) { return __hip_atomic_fetch_add(p, v, __ATOMIC_RELAXED, __HIP_MEMORY_SCOPE_AGENT); }
; #define XB_SPIN(cond, bar) do { unsigned _sp = 0; while (cond) { __builtin_amdgcn_s_sleep(1); \
;     if ((++_sp & 255u) == 0u) { if (xb_ld(&(bar)[XB_TMO])) break; if (_sp > XB_SPIN_CAP) { atomicAdd(&(bar)[XB_TMO], 1u); break; } } } } while (0)
; __device__ __forceinline__ void xcd_barrier(const XcdBarrier& b, const bool leader) {
;     ...
;     if (leader) {
;         unsigned* bar = b.bar;
;         __builtin_amdgcn_s_waitcnt(0);
;         unsigned nloc = b.st[0], nx = b.st[1];
;         if (nloc == 0u) { xcd_barrier_complete(bar, b.x, nloc, nx); b.st[0] = nloc; b.st[1] = nx; }
;         const unsigned old = xb_add(&bar[XB_XSUB(b.x)], 1u);
;         const unsigned gen = old / nloc;
;         if (old + 1u == (gen + 1u) * nloc) {
;             __builtin_amdgcn_fence(__ATOMIC_RELEASE, "agent");
;             asm volatile("s_waitcnt vmcnt(0)" ::: "memory");
;             const unsigned og = xb_add(&bar[XB_TOP], 1u);
;             const unsigned tg = og / nx;
;             if (og + 1u == (tg + 1u) * nx) xb_add(&bar[XB_TOPGEN], 1u);
;             else XB_SPIN(xb_ld(&bar[XB_TOPGEN]) == tg, bar);
;             __builtin_amdgcn_fence(__ATOMIC_ACQUIRE, "agent");
;             xb_add(&bar[XB_XGEN(b.x)], 1u);
;             asm volatile("s_waitcnt vmcnt(0)" ::: "memory");
;         } else {
;             XB_SPIN(xb_ld(&bar[XB_XGEN(b.x)]) == gen, bar);
;             __builtin_amdgcn_fence(__ATOMIC_ACQUIRE, "agent");
;             asm volatile("s_waitcnt vmcnt(0)" ::: "memory");
;         }
.LBB0_310:
	s_or_b64 exec, exec, s[12:13]
	v_cvt_f32_u32_e32 v6, v4
	s_waitcnt vmcnt(0)
	v_readfirstlane_b32 s1, v5
	v_sub_u32_e32 v5, 0, v4
	v_rcp_iflag_f32_e32 v6, v6
	v_add_u32_e32 v7, s1, v3
	v_mul_f32_e32 v6, 0x4f7ffffe, v6
	v_cvt_u32_f32_e32 v6, v6
	v_mul_lo_u32 v3, v5, v6
	v_mul_hi_u32 v3, v6, v3
	v_add_u32_e32 v3, v6, v3
	v_mul_hi_u32 v3, v7, v3
	v_mul_lo_u32 v5, v3, v4
	v_sub_u32_e32 v5, v7, v5
	v_add_u32_e32 v6, 1, v3
	v_cmp_ge_u32_e32 vcc, v5, v4
	s_nop 1
	v_cndmask_b32_e32 v3, v3, v6, vcc
	v_sub_u32_e32 v6, v5, v4
	v_cndmask_b32_e32 v5, v5, v6, vcc
	v_add_u32_e32 v6, 1, v3
	v_cmp_ge_u32_e32 vcc, v5, v4
	v_add_u32_e32 v5, 1, v7
	s_nop 0
	v_cndmask_b32_e32 v3, v3, v6, vcc
	v_mul_lo_u32 v6, v4, v3
	v_add_u32_e32 v4, v6, v4
	v_add_u32_e32 v6, 1, v6
	v_cmp_eq_u32_e32 vcc, v5, v6
	s_cbranch_vccz .Lewb_2
	buffer_wbl2 sc1
.Lewb_2:
	v_cmp_ne_u32_e32 vcc, v5, v4
	s_and_saveexec_b64 s[2:3], vcc
	s_xor_b64 s[10:11], exec, s[2:3]
	s_cbranch_execz .LBB0_324
	s_waitcnt lgkmcnt(0)
	v_mov_b32_e32 v2, 0x2000
	s_load_dwordx2 s[16:17], s[90:91], 0xb0
	s_waitcnt lgkmcnt(0)
	s_add_u32 s16, s16, 0x1d79b500
	s_addc_u32 s17, s17, 0
	v_mov_b32_e32 v2, 0
	global_load_dword v2, v2, s[16:17] sc1
	s_waitcnt vmcnt(0)
	v_cmp_eq_u32_e32 vcc, v2, v3
	s_and_saveexec_b64 s[12:13], vcc
	s_cbranch_execz .LBB0_323
	s_add_u32 s14, s4, 0x1d798200
	s_addc_u32 s15, s5, 0
	s_mov_b32 s1, 1
	s_mov_b64 s[18:19], 0
	v_mov_b32_e32 v2, 0
	s_branch .LBB0_314

; template <class Epi, class Sched, bool ALIGN_EPI = false, bool SP2 = false>
; __device__ __forceinline__ void gemm_phase(PG8_LAS unsigned char* lds, const Gemm g, const Sched& S, const Epi& E, const int tid_arg) {
;     ...
;         const bool has_next = S.next(ui + 1, nxt);
;         const char* nA = has_next ? (const char*)g.A + (size_t)nxt.pm * tstep : cA; const char* nB = has_next ? (const char*)g.Bt + (size_t)nxt.pn * tstep : cB;
;     ...
; #pragma unroll
;         for (int a = 0; a < 2; ++a)
; #pragma unroll
;             for (int b = 0; b < 2; ++b)
; #pragma unroll
;                 for (int m = 0; m < 4; ++m)
; #pragma unroll
;                     for (int n = 0; n < 2; ++n) acc[a][b][m][n] = (f32x4){0.f, 0.f, 0.f, 0.f};
.LBB0_362:
	s_ashr_i32 s29, s28, 31
	s_lshl_b64 s[6:7], s[28:29], 19
	s_add_u32 s30, s50, s6
	s_addc_u32 s31, s51, s7
	s_and_b64 s[6:7], s[8:9], exec
	s_cselect_b32 s6, s31, s15
	s_cselect_b32 s7, s30, s14
	s_ashr_i32 s27, s26, 31
	s_lshl_b64 s[34:35], s[26:27], 19
	s_add_u32 s34, s52, s34
	s_addc_u32 s35, s53, s35
	s_and_b64 s[38:39], s[8:9], exec
	s_cselect_b32 s11, s35, s37
	s_cselect_b32 s13, s34, s36
	s_add_u32 s14, s14, 0x40080
	s_addc_u32 s15, s15, 0
	s_add_u32 s27, s36, 0x100
	v_mov_b32_e32 v4, 0
	s_addc_u32 s29, s37, 0
	s_mov_b32 s40, -2
	v_mov_b32_e32 v5, v4
	v_mov_b32_e32 v6, v4
	v_mov_b32_e32 v7, v4
	v_mov_b32_e32 v8, v4
	v_mov_b32_e32 v9, v4
	v_mov_b32_e32 v10, v4
	v_mov_b32_e32 v11, v4
	v_mov_b32_e32 v20, v4
	v_mov_b32_e32 v21, v4
	v_mov_b32_e32 v22, v4
	v_mov_b32_e32 v23, v4
	v_mov_b32_e32 v24, v4
	v_mov_b32_e32 v25, v4
	v_mov_b32_e32 v26, v4
	v_mov_b32_e32 v27, v4
	v_mov_b32_e32 v36, v4
	v_mov_b32_e32 v37, v4
	v_mov_b32_e32 v38, v4
	v_mov_b32_e32 v39, v4
	v_mov_b32_e32 v40, v4
	v_mov_b32_e32 v41, v4
	v_mov_b32_e32 v42, v4
	v_mov_b32_e32 v43, v4
	v_mov_b32_e32 v52, v4
	v_mov_b32_e32 v53, v4
	v_mov_b32_e32 v54, v4
	v_mov_b32_e32 v55, v4
	v_mov_b32_e32 v56, v4
	v_mov_b32_e32 v57, v4
	v_mov_b32_e32 v58, v4
	v_mov_b32_e32 v59, v4
	v_mov_b32_e32 v12, v4
	v_mov_b32_e32 v13, v4
	v_mov_b32_e32 v14, v4
	v_mov_b32_e32 v15, v4
	v_mov_b32_e32 v16, v4
	v_mov_b32_e32 v17, v4
	v_mov_b32_e32 v18, v4
	v_mov_b32_e32 v19, v4
	v_mov_b32_e32 v28, v4
	v_mov_b32_e32 v29, v4
	v_mov_b32_e32 v30, v4
	v_mov_b32_e32 v31, v4
	v_mov_b32_e32 v32, v4
	v_mov_b32_e32 v33, v4
	v_mov_b32_e32 v34, v4
	v_mov_b32_e32 v35, v4
	v_mov_b32_e32 v44, v4
	v_mov_b32_e32 v45, v4
	v_mov_b32_e32 v46, v4
	v_mov_b32_e32 v47, v4
	v_mov_b32_e32 v48, v4
	v_mov_b32_e32 v49, v4
	v_mov_b32_e32 v50, v4
	v_mov_b32_e32 v51, v4
	v_mov_b32_e32 v60, v4
	v_mov_b32_e32 v61, v4
	v_mov_b32_e32 v62, v4
	v_mov_b32_e32 v63, v4
	v_mov_b32_e32 v64, v4
	v_mov_b32_e32 v65, v4
	v_mov_b32_e32 v66, v4
	v_mov_b32_e32 v67, v4
	v_mov_b32_e32 v68, v4
	v_mov_b32_e32 v69, v4
	v_mov_b32_e32 v70, v4
	v_mov_b32_e32 v71, v4
	v_mov_b32_e32 v72, v4
	v_mov_b32_e32 v73, v4
	v_mov_b32_e32 v74, v4
	v_mov_b32_e32 v75, v4
	v_mov_b32_e32 v84, v4
	v_mov_b32_e32 v85, v4
	v_mov_b32_e32 v86, v4
	v_mov_b32_e32 v87, v4
	v_mov_b32_e32 v88, v4
	v_mov_b32_e32 v89, v4
	v_mov_b32_e32 v90, v4
	v_mov_b32_e32 v91, v4
	v_mov_b32_e32 v100, v4
	v_mov_b32_e32 v101, v4
	v_mov_b32_e32 v102, v4
	v_mov_b32_e32 v103, v4
	v_mov_b32_e32 v104, v4
	v_mov_b32_e32 v105, v4
	v_mov_b32_e32 v106, v4
	v_mov_b32_e32 v107, v4
	v_mov_b32_e32 v116, v4
	v_mov_b32_e32 v117, v4
	v_mov_b32_e32 v118, v4
	v_mov_b32_e32 v119, v4
	s_waitcnt vmcnt(0)
	v_mov_b32_e32 v120, v4
	v_mov_b32_e32 v121, v4
	v_mov_b32_e32 v122, v4
	v_mov_b32_e32 v123, v4
	v_mov_b32_e32 v76, v4
	v_mov_b32_e32 v77, v4
	v_mov_b32_e32 v78, v4
	v_mov_b32_e32 v79, v4
	v_mov_b32_e32 v80, v4
	v_mov_b32_e32 v81, v4
	v_mov_b32_e32 v82, v4
	v_mov_b32_e32 v83, v4
	v_mov_b32_e32 v92, v4
	v_mov_b32_e32 v93, v4
	v_mov_b32_e32 v94, v4
	v_mov_b32_e32 v95, v4
	v_mov_b32_e32 v96, v4
	v_mov_b32_e32 v97, v4
	v_mov_b32_e32 v98, v4
	v_mov_b32_e32 v99, v4
	v_mov_b32_e32 v108, v4
	v_mov_b32_e32 v109, v4
	v_mov_b32_e32 v110, v4
	v_mov_b32_e32 v111, v4
	v_mov_b32_e32 v112, v4
	v_mov_b32_e32 v113, v4
	v_mov_b32_e32 v114, v4
	v_mov_b32_e32 v115, v4
	v_mov_b32_e32 v124, v4
	v_mov_b32_e32 v125, v4
	v_mov_b32_e32 v126, v4
	v_mov_b32_e32 v127, v4
	v_mov_b32_e32 v128, v4
	v_mov_b32_e32 v129, v4
	v_mov_b32_e32 v130, v4
	v_mov_b32_e32 v131, v4
	s_nop 0
	s_nop 0
	s_nop 0
	s_nop 0
	s_nop 0
	s_nop 0
	s_nop 0
	s_nop 0
	s_nop 0
	s_nop 0
	s_nop 0

; __device__ __forceinline__ unsigned xb_ld(unsigned* p)              { return __hip_atomic_load(p, __ATOMIC_RELAXED, __HIP_MEMORY_SCOPE_AGENT); }
; __device__ __forceinline__ unsigned xb_add(unsigned* p, unsigned v) { return __hip_atomic_fetch_add(p, v, __ATOMIC_RELAXED, __HIP_MEMORY_SCOPE_AGENT); }
; #define XB_SPIN(cond, bar) do { unsigned _sp = 0; while (cond) { __builtin_amdgcn_s_sleep(1); \
;     if ((++_sp & 255u) == 0u) { if (xb_ld(&(bar)[XB_TMO])) break; if (_sp > XB_SPIN_CAP) { atomicAdd(&(bar)[XB_TMO], 1u); break; } } } } while (0)
; __device__ __forceinline__ void xcd_barrier(const XcdBarrier& b, const bool leader) {
;     ...
;         const unsigned old = xb_add(&bar[XB_XSUB(b.x)], 1u);
;         const unsigned gen = old / nloc;
;         if (old + 1u == (gen + 1u) * nloc) {
;             __builtin_amdgcn_fence(__ATOMIC_RELEASE, "agent");
;             asm volatile("s_waitcnt vmcnt(0)" ::: "memory");
;             const unsigned og = xb_add(&bar[XB_TOP], 1u);
;             const unsigned tg = og / nx;
;             if (og + 1u == (tg + 1u) * nx) xb_add(&bar[XB_TOPGEN], 1u);
;             else XB_SPIN(xb_ld(&bar[XB_TOPGEN]) == tg, bar);
;             __builtin_amdgcn_fence(__ATOMIC_ACQUIRE, "agent");
;             xb_add(&bar[XB_XGEN(b.x)], 1u);
;             asm volatile("s_waitcnt vmcnt(0)" ::: "memory");
;         } else {
;             XB_SPIN(xb_ld(&bar[XB_XGEN(b.x)]) == gen, bar);
.LBB0_470:
	s_or_b64 exec, exec, s[14:15]
	v_cvt_f32_u32_e32 v7, v5
	s_waitcnt vmcnt(0)
	v_readfirstlane_b32 s2, v6
	v_sub_u32_e32 v6, 0, v5
	v_rcp_iflag_f32_e32 v7, v7
	v_add_u32_e32 v8, s2, v2
	v_mul_f32_e32 v7, 0x4f7ffffe, v7
	v_cvt_u32_f32_e32 v7, v7
	v_mul_lo_u32 v2, v6, v7
	v_mul_hi_u32 v2, v7, v2
	v_add_u32_e32 v2, v7, v2
	v_mul_hi_u32 v2, v8, v2
	v_mul_lo_u32 v6, v2, v5
	v_sub_u32_e32 v6, v8, v6
	v_add_u32_e32 v7, 1, v2
	v_cmp_ge_u32_e32 vcc, v6, v5
	s_nop 1
	v_cndmask_b32_e32 v2, v2, v7, vcc
	v_sub_u32_e32 v7, v6, v5
	v_cndmask_b32_e32 v6, v6, v7, vcc
	v_add_u32_e32 v7, 1, v2
	v_cmp_ge_u32_e32 vcc, v6, v5
	v_add_u32_e32 v6, 1, v8
	s_nop 0
	v_cndmask_b32_e32 v2, v2, v7, vcc
	v_mul_lo_u32 v7, v5, v2
	v_add_u32_e32 v5, v7, v5
	v_add_u32_e32 v7, 1, v7
	v_cmp_eq_u32_e32 vcc, v6, v7
	s_cbranch_vccz .Lewb_3
	buffer_wbl2 sc1
.Lewb_3:
	v_cmp_ne_u32_e32 vcc, v6, v5
	s_and_saveexec_b64 s[2:3], vcc
	s_xor_b64 s[12:13], exec, s[2:3]
	s_cbranch_execz .LBB0_484
	s_waitcnt lgkmcnt(0)
	s_load_dwordx2 s[20:21], s[90:91], 0xb0
	s_waitcnt lgkmcnt(0)
	s_add_u32 s20, s20, 0x1d79b500
	s_addc_u32 s21, s21, 0
	v_mov_b32_e32 v4, 0
	global_load_dword v4, v4, s[20:21] sc1
	s_waitcnt vmcnt(0)
	v_cmp_eq_u32_e32 vcc, v4, v2
	s_and_saveexec_b64 s[14:15], vcc
	s_cbranch_execz .LBB0_483
	s_add_u32 s16, s18, 0x1d798200
	s_addc_u32 s17, s19, 0
	s_mov_b32 s2, 1
	s_mov_b64 s[22:23], 0
	s_branch .LBB0_474

; __device__ __forceinline__ unsigned xb_ld(unsigned* p)              { return __hip_atomic_load(p, __ATOMIC_RELAXED, __HIP_MEMORY_SCOPE_AGENT); }
; __device__ __forceinline__ unsigned xb_add(unsigned* p, unsigned v) { return __hip_atomic_fetch_add(p, v, __ATOMIC_RELAXED, __HIP_MEMORY_SCOPE_AGENT); }
; #define XB_SPIN(cond, bar) do { unsigned _sp = 0; while (cond) { __builtin_amdgcn_s_sleep(1); \
;     if ((++_sp & 255u) == 0u) { if (xb_ld(&(bar)[XB_TMO])) break; if (_sp > XB_SPIN_CAP) { atomicAdd(&(bar)[XB_TMO], 1u); break; } } } } while (0)
; __device__ __forceinline__ void xcd_barrier(const XcdBarrier& b, const bool leader) {
;     ...
;         const unsigned old = xb_add(&bar[XB_XSUB(b.x)], 1u);
;         const unsigned gen = old / nloc;
;         if (old + 1u == (gen + 1u) * nloc) {
;             __builtin_amdgcn_fence(__ATOMIC_RELEASE, "agent");
;             asm volatile("s_waitcnt vmcnt(0)" ::: "memory");
;             const unsigned og = xb_add(&bar[XB_TOP], 1u);
;             const unsigned tg = og / nx;
;             if (og + 1u == (tg + 1u) * nx) xb_add(&bar[XB_TOPGEN], 1u);
;             else XB_SPIN(xb_ld(&bar[XB_TOPGEN]) == tg, bar);
;             __builtin_amdgcn_fence(__ATOMIC_ACQUIRE, "agent");
;             xb_add(&bar[XB_XGEN(b.x)], 1u);
;             asm volatile("s_waitcnt vmcnt(0)" ::: "memory");
;         } else {
;             XB_SPIN(xb_ld(&bar[XB_XGEN(b.x)]) == gen, bar);
.LBB0_582:
	s_or_b64 exec, exec, s[12:13]
	v_cvt_f32_u32_e32 v7, v5
	s_waitcnt vmcnt(0)
	v_readfirstlane_b32 s2, v6
	v_sub_u32_e32 v6, 0, v5
	v_rcp_iflag_f32_e32 v7, v7
	v_add_u32_e32 v8, s2, v2
	v_mul_f32_e32 v7, 0x4f7ffffe, v7
	v_cvt_u32_f32_e32 v7, v7
	v_mul_lo_u32 v2, v6, v7
	v_mul_hi_u32 v2, v7, v2
	v_add_u32_e32 v2, v7, v2
	v_mul_hi_u32 v2, v8, v2
	v_mul_lo_u32 v6, v2, v5
	v_sub_u32_e32 v6, v8, v6
	v_add_u32_e32 v7, 1, v2
	v_cmp_ge_u32_e32 vcc, v6, v5
	s_nop 1
	v_cndmask_b32_e32 v2, v2, v7, vcc
	v_sub_u32_e32 v7, v6, v5
	v_cndmask_b32_e32 v6, v6, v7, vcc
	v_add_u32_e32 v7, 1, v2
	v_cmp_ge_u32_e32 vcc, v6, v5
	v_add_u32_e32 v6, 1, v8
	s_nop 0
	v_cndmask_b32_e32 v2, v2, v7, vcc
	v_mul_lo_u32 v7, v5, v2
	v_add_u32_e32 v5, v7, v5
	v_add_u32_e32 v7, 1, v7
	v_cmp_eq_u32_e32 vcc, v6, v7
	s_cbranch_vccz .Lewb_4
	buffer_wbl2 sc1
.Lewb_4:
	v_cmp_ne_u32_e32 vcc, v6, v5
	s_and_saveexec_b64 s[2:3], vcc
	s_xor_b64 s[10:11], exec, s[2:3]
	s_cbranch_execz .LBB0_596
	s_waitcnt lgkmcnt(0)
	s_load_dwordx2 s[16:17], s[90:91], 0xb0
	s_waitcnt lgkmcnt(0)
	s_add_u32 s16, s16, 0x1d79b500
	s_addc_u32 s17, s17, 0
	v_mov_b32_e32 v4, 0
	global_load_dword v4, v4, s[16:17] sc1
	s_waitcnt vmcnt(0)
	v_cmp_eq_u32_e32 vcc, v4, v2
	s_and_saveexec_b64 s[12:13], vcc
	s_cbranch_execz .LBB0_595
	s_add_u32 s14, s50, 0x1d798200
	s_addc_u32 s15, s51, 0
	s_mov_b32 s2, 1
	s_mov_b64 s[18:19], 0
	s_branch .LBB0_586

; __device__ __forceinline__ unsigned xb_ld(unsigned* p)              { return __hip_atomic_load(p, __ATOMIC_RELAXED, __HIP_MEMORY_SCOPE_AGENT); }
; __device__ __forceinline__ unsigned xb_add(unsigned* p, unsigned v) { return __hip_atomic_fetch_add(p, v, __ATOMIC_RELAXED, __HIP_MEMORY_SCOPE_AGENT); }
; #define XB_SPIN(cond, bar) do { unsigned _sp = 0; while (cond) { __builtin_amdgcn_s_sleep(1); \
;     if ((++_sp & 255u) == 0u) { if (xb_ld(&(bar)[XB_TMO])) break; if (_sp > XB_SPIN_CAP) { atomicAdd(&(bar)[XB_TMO], 1u); break; } } } } while (0)
; __device__ __forceinline__ void xcd_barrier(const XcdBarrier& b, const bool leader) {
;     ...
;         const unsigned old = xb_add(&bar[XB_XSUB(b.x)], 1u);
;         const unsigned gen = old / nloc;
;         if (old + 1u == (gen + 1u) * nloc) {
;             __builtin_amdgcn_fence(__ATOMIC_RELEASE, "agent");
;             asm volatile("s_waitcnt vmcnt(0)" ::: "memory");
;             const unsigned og = xb_add(&bar[XB_TOP], 1u);
;             const unsigned tg = og / nx;
;             if (og + 1u == (tg + 1u) * nx) xb_add(&bar[XB_TOPGEN], 1u);
;             else XB_SPIN(xb_ld(&bar[XB_TOPGEN]) == tg, bar);
;             __builtin_amdgcn_fence(__ATOMIC_ACQUIRE, "agent");
;             xb_add(&bar[XB_XGEN(b.x)], 1u);
;             asm volatile("s_waitcnt vmcnt(0)" ::: "memory");
;         } else {
;             XB_SPIN(xb_ld(&bar[XB_XGEN(b.x)]) == gen, bar);
.LBB0_660:
	s_or_b64 exec, exec, s[6:7]
	v_cvt_f32_u32_e32 v7, v5
	s_waitcnt vmcnt(0)
	v_readfirstlane_b32 s2, v6
	v_sub_u32_e32 v6, 0, v5
	v_rcp_iflag_f32_e32 v7, v7
	v_add_u32_e32 v8, s2, v2
	v_mul_f32_e32 v7, 0x4f7ffffe, v7
	v_cvt_u32_f32_e32 v7, v7
	v_mul_lo_u32 v2, v6, v7
	v_mul_hi_u32 v2, v7, v2
	v_add_u32_e32 v2, v7, v2
	v_mul_hi_u32 v2, v8, v2
	v_mul_lo_u32 v6, v2, v5
	v_sub_u32_e32 v6, v8, v6
	v_add_u32_e32 v7, 1, v2
	v_cmp_ge_u32_e32 vcc, v6, v5
	s_nop 1
	v_cndmask_b32_e32 v2, v2, v7, vcc
	v_sub_u32_e32 v7, v6, v5
	v_cndmask_b32_e32 v6, v6, v7, vcc
	v_add_u32_e32 v7, 1, v2
	v_cmp_ge_u32_e32 vcc, v6, v5
	v_add_u32_e32 v6, 1, v8
	s_nop 0
	v_cndmask_b32_e32 v2, v2, v7, vcc
	v_mul_lo_u32 v7, v5, v2
	v_add_u32_e32 v5, v7, v5
	v_add_u32_e32 v7, 1, v7
	v_cmp_eq_u32_e32 vcc, v6, v7
	s_cbranch_vccz .Lewb_5
	buffer_wbl2 sc1
.Lewb_5:
	v_cmp_ne_u32_e32 vcc, v6, v5
	s_and_saveexec_b64 s[2:3], vcc
	s_xor_b64 s[12:13], exec, s[2:3]
	s_cbranch_execz .LBB0_674
	s_waitcnt lgkmcnt(0)
	s_load_dwordx2 s[18:19], s[90:91], 0xb0
	s_waitcnt lgkmcnt(0)
	s_add_u32 s18, s18, 0x1d79b500
	s_addc_u32 s19, s19, 0
	v_mov_b32_e32 v4, 0
	global_load_dword v4, v4, s[18:19] sc1
	s_waitcnt vmcnt(0)
	v_cmp_eq_u32_e32 vcc, v4, v2
	s_and_saveexec_b64 s[14:15], vcc
	s_cbranch_execz .LBB0_673
	s_add_u32 s16, s4, 0x1d798200
	s_addc_u32 s17, s5, 0
	s_mov_b32 s2, 1
	s_mov_b64 s[20:21], 0
	s_branch .LBB0_664

; template <class Epi, class Sched, bool ALIGN_EPI = false, bool SP2 = false>
; __device__ __forceinline__ void gemm_phase(PG8_LAS unsigned char* lds, const Gemm g, const Sched& S, const Epi& E, const int tid_arg) {
;     ...
;         const bool has_next = S.next(ui + 1, nxt);
;         const char* nA = has_next ? (const char*)g.A + (size_t)nxt.pm * tstep : cA; const char* nB = has_next ? (const char*)g.Bt + (size_t)nxt.pn * tstep : cB;
;     ...
; #pragma unroll
;         for (int a = 0; a < 2; ++a)
; #pragma unroll
;             for (int b = 0; b < 2; ++b)
; #pragma unroll
;                 for (int m = 0; m < 4; ++m)
; #pragma unroll
;                     for (int n = 0; n < 2; ++n) acc[a][b][m][n] = (f32x4){0.f, 0.f, 0.f, 0.f};
.LBB0_763:
	s_ashr_i32 s27, s26, 31
	s_lshl_b64 s[28:29], s[26:27], 19
	s_add_u32 s28, s3, s28
	s_addc_u32 s29, s6, s29
	s_and_b64 s[30:31], s[10:11], exec
	s_cselect_b32 s27, s29, s5
	s_cselect_b32 s48, s28, s4
	s_ashr_i32 s25, s24, 31
	s_lshl_b64 s[30:31], s[24:25], 19
	s_add_u32 s30, s7, s30
	s_addc_u32 s31, s38, s31
	s_and_b64 s[36:37], s[10:11], exec
	s_cselect_b32 s25, s31, s35
	s_cselect_b32 s49, s30, s34
	s_add_u32 s4, s4, 0x40080
	s_addc_u32 s5, s5, 0
	s_add_u32 s50, s34, 0x100
	v_mov_b32_e32 v4, 0
	s_addc_u32 s51, s35, 0
	s_mov_b32 s52, -2
	v_mov_b32_e32 v5, v4
	v_mov_b32_e32 v6, v4
	v_mov_b32_e32 v7, v4
	v_mov_b32_e32 v8, v4
	v_mov_b32_e32 v9, v4
	v_mov_b32_e32 v10, v4
	v_mov_b32_e32 v11, v4
	v_mov_b32_e32 v20, v4
	v_mov_b32_e32 v21, v4
	v_mov_b32_e32 v22, v4
	v_mov_b32_e32 v23, v4
	v_mov_b32_e32 v24, v4
	v_mov_b32_e32 v25, v4
	v_mov_b32_e32 v26, v4
	v_mov_b32_e32 v27, v4
	v_mov_b32_e32 v36, v4
	v_mov_b32_e32 v37, v4
	v_mov_b32_e32 v38, v4
	v_mov_b32_e32 v39, v4
	v_mov_b32_e32 v40, v4
	v_mov_b32_e32 v41, v4
	v_mov_b32_e32 v42, v4
	v_mov_b32_e32 v43, v4
	v_mov_b32_e32 v52, v4
	v_mov_b32_e32 v53, v4
	v_mov_b32_e32 v54, v4
	v_mov_b32_e32 v55, v4
	v_mov_b32_e32 v56, v4
	v_mov_b32_e32 v57, v4
	v_mov_b32_e32 v58, v4
	v_mov_b32_e32 v59, v4
	v_mov_b32_e32 v12, v4
	v_mov_b32_e32 v13, v4
	v_mov_b32_e32 v14, v4
	v_mov_b32_e32 v15, v4
	v_mov_b32_e32 v16, v4
	v_mov_b32_e32 v17, v4
	v_mov_b32_e32 v18, v4
	v_mov_b32_e32 v19, v4
	v_mov_b32_e32 v28, v4
	v_mov_b32_e32 v29, v4
	v_mov_b32_e32 v30, v4
	v_mov_b32_e32 v31, v4
	v_mov_b32_e32 v32, v4
	v_mov_b32_e32 v33, v4
	v_mov_b32_e32 v34, v4
	v_mov_b32_e32 v35, v4
	v_mov_b32_e32 v44, v4
	v_mov_b32_e32 v45, v4
	v_mov_b32_e32 v46, v4
	v_mov_b32_e32 v47, v4
	v_mov_b32_e32 v48, v4
	v_mov_b32_e32 v49, v4
	v_mov_b32_e32 v50, v4
	v_mov_b32_e32 v51, v4
	v_mov_b32_e32 v60, v4
	v_mov_b32_e32 v61, v4
	v_mov_b32_e32 v62, v4
	v_mov_b32_e32 v63, v4
	v_mov_b32_e32 v64, v4
	v_mov_b32_e32 v65, v4
	v_mov_b32_e32 v66, v4
	v_mov_b32_e32 v67, v4
	v_mov_b32_e32 v68, v4
	v_mov_b32_e32 v69, v4
	v_mov_b32_e32 v70, v4
	v_mov_b32_e32 v71, v4
	v_mov_b32_e32 v72, v4
	v_mov_b32_e32 v73, v4
	v_mov_b32_e32 v74, v4
	v_mov_b32_e32 v75, v4
	v_mov_b32_e32 v84, v4
	v_mov_b32_e32 v85, v4
	v_mov_b32_e32 v86, v4
	v_mov_b32_e32 v87, v4
	v_mov_b32_e32 v88, v4
	v_mov_b32_e32 v89, v4
	v_mov_b32_e32 v90, v4
	v_mov_b32_e32 v91, v4
	v_mov_b32_e32 v100, v4
	v_mov_b32_e32 v101, v4
	v_mov_b32_e32 v102, v4
	v_mov_b32_e32 v103, v4
	v_mov_b32_e32 v104, v4
	v_mov_b32_e32 v105, v4
	v_mov_b32_e32 v106, v4
	v_mov_b32_e32 v107, v4
	v_mov_b32_e32 v116, v4
	v_mov_b32_e32 v117, v4
	v_mov_b32_e32 v118, v4
	v_mov_b32_e32 v119, v4
	s_waitcnt vmcnt(0)
	v_mov_b32_e32 v120, v4
	v_mov_b32_e32 v121, v4
	v_mov_b32_e32 v122, v4
	v_mov_b32_e32 v123, v4
	v_mov_b32_e32 v76, v4
	v_mov_b32_e32 v77, v4
	v_mov_b32_e32 v78, v4
	v_mov_b32_e32 v79, v4
	v_mov_b32_e32 v80, v4
	v_mov_b32_e32 v81, v4
	v_mov_b32_e32 v82, v4
	v_mov_b32_e32 v83, v4
	v_mov_b32_e32 v92, v4
	v_mov_b32_e32 v93, v4
	v_mov_b32_e32 v94, v4
	v_mov_b32_e32 v95, v4
	v_mov_b32_e32 v96, v4
	v_mov_b32_e32 v97, v4
	v_mov_b32_e32 v98, v4
	v_mov_b32_e32 v99, v4
	v_mov_b32_e32 v108, v4
	v_mov_b32_e32 v109, v4
	v_mov_b32_e32 v110, v4
	v_mov_b32_e32 v111, v4
	v_mov_b32_e32 v112, v4
	v_mov_b32_e32 v113, v4
	v_mov_b32_e32 v114, v4
	v_mov_b32_e32 v115, v4
	v_mov_b32_e32 v124, v4
	v_mov_b32_e32 v125, v4
	v_mov_b32_e32 v126, v4
	v_mov_b32_e32 v127, v4
	v_mov_b32_e32 v128, v4
	v_mov_b32_e32 v129, v4
	v_mov_b32_e32 v130, v4
	v_mov_b32_e32 v131, v4
	s_nop 0
	s_nop 0
	s_nop 0
	s_nop 0
	s_nop 0
	s_nop 0
	s_nop 0
	s_nop 0
	s_nop 0
	s_nop 0
	s_nop 0
	s_nop 0
	s_nop 0
	s_nop 0
	s_nop 0
	s_nop 0
	s_nop 0
	s_nop 0
	s_nop 0
	s_nop 0

; __device__ __forceinline__ unsigned xb_ld(unsigned* p)              { return __hip_atomic_load(p, __ATOMIC_RELAXED, __HIP_MEMORY_SCOPE_AGENT); }
; __device__ __forceinline__ unsigned xb_add(unsigned* p, unsigned v) { return __hip_atomic_fetch_add(p, v, __ATOMIC_RELAXED, __HIP_MEMORY_SCOPE_AGENT); }
; #define XB_SPIN(cond, bar) do { unsigned _sp = 0; while (cond) { __builtin_amdgcn_s_sleep(1); \
;     if ((++_sp & 255u) == 0u) { if (xb_ld(&(bar)[XB_TMO])) break; if (_sp > XB_SPIN_CAP) { atomicAdd(&(bar)[XB_TMO], 1u); break; } } } } while (0)
; __device__ __forceinline__ void xcd_barrier(const XcdBarrier& b, const bool leader) {
;     ...
;         if (old + 1u == (gen + 1u) * nloc) {
;             __builtin_amdgcn_fence(__ATOMIC_RELEASE, "agent");
;             asm volatile("s_waitcnt vmcnt(0)" ::: "memory");
;             const unsigned og = xb_add(&bar[XB_TOP], 1u);
;             const unsigned tg = og / nx;
;             if (og + 1u == (tg + 1u) * nx) xb_add(&bar[XB_TOPGEN], 1u);
;             else XB_SPIN(xb_ld(&bar[XB_TOPGEN]) == tg, bar);
;             __builtin_amdgcn_fence(__ATOMIC_ACQUIRE, "agent");
;             xb_add(&bar[XB_XGEN(b.x)], 1u);
;             asm volatile("s_waitcnt vmcnt(0)" ::: "memory");
;         } else {
;             XB_SPIN(xb_ld(&bar[XB_XGEN(b.x)]) == gen, bar);
.Lewb_7:
	v_cmp_ne_u32_e32 vcc, v6, v5
	s_and_saveexec_b64 s[2:3], vcc
	s_xor_b64 s[16:17], exec, s[2:3]
	s_cbranch_execz .LBB0_835
	s_waitcnt lgkmcnt(0)
	s_load_dwordx2 s[22:23], s[90:91], 0xb0
	s_waitcnt lgkmcnt(0)
	s_add_u32 s22, s22, 0x1d79b500
	s_addc_u32 s23, s23, 0
	v_mov_b32_e32 v4, 0
	global_load_dword v4, v4, s[22:23] sc1
	s_waitcnt vmcnt(0)
	v_cmp_eq_u32_e32 vcc, v4, v2
	s_and_saveexec_b64 s[18:19], vcc
	s_cbranch_execz .LBB0_834
	s_add_u32 s20, s12, 0x1d798200
	s_addc_u32 s21, s13, 0
	s_mov_b32 s2, 1
	s_mov_b64 s[24:25], 0
	s_branch .LBB0_825

; template <class Epi, class Sched, bool ALIGN_EPI = false, bool SP2 = false>
; __device__ __forceinline__ void gemm_phase(PG8_LAS unsigned char* lds, const Gemm g, const Sched& S, const Epi& E, const int tid_arg) {
;     ...
;         const bool has_next = S.next(ui + 1, nxt);
;         const char* nA = has_next ? (const char*)g.A + (size_t)nxt.pm * tstep : cA; const char* nB = has_next ? (const char*)g.Bt + (size_t)nxt.pn * tstep : cB;
;     ...
; #pragma unroll
;         for (int a = 0; a < 2; ++a)
; #pragma unroll
;             for (int b = 0; b < 2; ++b)
; #pragma unroll
;                 for (int m = 0; m < 4; ++m)
; #pragma unroll
;                     for (int n = 0; n < 2; ++n) acc[a][b][m][n] = (f32x4){0.f, 0.f, 0.f, 0.f};
.LBB0_867:
	s_ashr_i32 s35, s34, 31
	s_lshl_b64 s[36:37], s[34:35], 19
	s_add_u32 s36, s2, s36
	s_addc_u32 s37, s47, s37
	s_and_b64 s[38:39], s[14:15], exec
	s_cselect_b32 s7, s37, s17
	s_cselect_b32 s35, s36, s16
	s_ashr_i32 s31, s30, 31
	s_lshl_b64 s[38:39], s[30:31], 19
	s_add_u32 s38, s48, s38
	s_addc_u32 s39, s49, s39
	s_and_b64 s[44:45], s[14:15], exec
	s_cselect_b32 s31, s39, s43
	s_cselect_b32 s41, s38, s42
	s_add_u32 s16, s16, 0x40080
	s_addc_u32 s17, s17, 0
	s_add_u32 s59, s42, 0x100
	v_mov_b32_e32 v4, 0
	s_addc_u32 s60, s43, 0
	s_mov_b32 s61, -2
	s_waitcnt lgkmcnt(0)
	v_mov_b32_e32 v5, v4
	v_mov_b32_e32 v6, v4
	v_mov_b32_e32 v7, v4
	v_mov_b32_e32 v8, v4
	v_mov_b32_e32 v9, v4
	v_mov_b32_e32 v10, v4
	v_mov_b32_e32 v11, v4
	v_mov_b32_e32 v20, v4
	v_mov_b32_e32 v21, v4
	v_mov_b32_e32 v22, v4
	v_mov_b32_e32 v23, v4
	v_mov_b32_e32 v24, v4
	v_mov_b32_e32 v25, v4
	v_mov_b32_e32 v26, v4
	v_mov_b32_e32 v27, v4
	v_mov_b32_e32 v36, v4
	v_mov_b32_e32 v37, v4
	v_mov_b32_e32 v38, v4
	v_mov_b32_e32 v39, v4
	v_mov_b32_e32 v40, v4
	v_mov_b32_e32 v41, v4
	v_mov_b32_e32 v42, v4
	v_mov_b32_e32 v43, v4
	v_mov_b32_e32 v52, v4
	v_mov_b32_e32 v53, v4
	v_mov_b32_e32 v54, v4
	v_mov_b32_e32 v55, v4
	v_mov_b32_e32 v56, v4
	v_mov_b32_e32 v57, v4
	v_mov_b32_e32 v58, v4
	v_mov_b32_e32 v59, v4
	v_mov_b32_e32 v12, v4
	v_mov_b32_e32 v13, v4
	v_mov_b32_e32 v14, v4
	v_mov_b32_e32 v15, v4
	v_mov_b32_e32 v16, v4
	v_mov_b32_e32 v17, v4
	v_mov_b32_e32 v18, v4
	v_mov_b32_e32 v19, v4
	v_mov_b32_e32 v28, v4
	v_mov_b32_e32 v29, v4
	v_mov_b32_e32 v30, v4
	v_mov_b32_e32 v31, v4
	v_mov_b32_e32 v32, v4
	v_mov_b32_e32 v33, v4
	v_mov_b32_e32 v34, v4
	v_mov_b32_e32 v35, v4
	v_mov_b32_e32 v44, v4
	v_mov_b32_e32 v45, v4
	v_mov_b32_e32 v46, v4
	v_mov_b32_e32 v47, v4
	v_mov_b32_e32 v48, v4
	v_mov_b32_e32 v49, v4
	v_mov_b32_e32 v50, v4
	v_mov_b32_e32 v51, v4
	v_mov_b32_e32 v60, v4
	v_mov_b32_e32 v61, v4
	v_mov_b32_e32 v62, v4
	v_mov_b32_e32 v63, v4
	v_mov_b32_e32 v64, v4
	v_mov_b32_e32 v65, v4
	v_mov_b32_e32 v66, v4
	v_mov_b32_e32 v67, v4
	v_mov_b32_e32 v68, v4
	v_mov_b32_e32 v69, v4
	v_mov_b32_e32 v70, v4
	v_mov_b32_e32 v71, v4
	v_mov_b32_e32 v72, v4
	v_mov_b32_e32 v73, v4
	v_mov_b32_e32 v74, v4
	v_mov_b32_e32 v75, v4
	v_mov_b32_e32 v84, v4
	v_mov_b32_e32 v85, v4
	v_mov_b32_e32 v86, v4
	v_mov_b32_e32 v87, v4
	v_mov_b32_e32 v88, v4
	v_mov_b32_e32 v89, v4
	v_mov_b32_e32 v90, v4
	v_mov_b32_e32 v91, v4
	v_mov_b32_e32 v100, v4
	v_mov_b32_e32 v101, v4
	v_mov_b32_e32 v102, v4
	v_mov_b32_e32 v103, v4
	v_mov_b32_e32 v104, v4
	v_mov_b32_e32 v105, v4
	v_mov_b32_e32 v106, v4
	v_mov_b32_e32 v107, v4
	v_mov_b32_e32 v116, v4
	v_mov_b32_e32 v117, v4
	v_mov_b32_e32 v118, v4
	v_mov_b32_e32 v119, v4
	s_waitcnt vmcnt(0)
	v_mov_b32_e32 v120, v4
	v_mov_b32_e32 v121, v4
	v_mov_b32_e32 v122, v4
	v_mov_b32_e32 v123, v4
	v_mov_b32_e32 v76, v4
	v_mov_b32_e32 v77, v4
	v_mov_b32_e32 v78, v4
	v_mov_b32_e32 v79, v4
	v_mov_b32_e32 v80, v4
	v_mov_b32_e32 v81, v4
	v_mov_b32_e32 v82, v4
	v_mov_b32_e32 v83, v4
	v_mov_b32_e32 v92, v4
	v_mov_b32_e32 v93, v4
	v_mov_b32_e32 v94, v4
	v_mov_b32_e32 v95, v4
	v_mov_b32_e32 v96, v4
	v_mov_b32_e32 v97, v4
	v_mov_b32_e32 v98, v4
	v_mov_b32_e32 v99, v4
	v_mov_b32_e32 v108, v4
	v_mov_b32_e32 v109, v4
	v_mov_b32_e32 v110, v4
	v_mov_b32_e32 v111, v4
	v_mov_b32_e32 v112, v4
	v_mov_b32_e32 v113, v4
	v_mov_b32_e32 v114, v4
	v_mov_b32_e32 v115, v4
	v_mov_b32_e32 v124, v4
	v_mov_b32_e32 v125, v4
	v_mov_b32_e32 v126, v4
	v_mov_b32_e32 v127, v4
	v_mov_b32_e32 v128, v4
	v_mov_b32_e32 v129, v4
	v_mov_b32_e32 v130, v4
	v_mov_b32_e32 v131, v4
	s_nop 0
	s_nop 0
	s_nop 0
	s_nop 0
	s_nop 0
	s_nop 0
	s_nop 0
	s_nop 0
	s_nop 0
	s_nop 0
	s_nop 0

; template <class Epi, class Sched, bool ALIGN_EPI = false, bool SP2 = false>
; __device__ __forceinline__ void gemm_phase(PG8_LAS unsigned char* lds, const Gemm g, const Sched& S, const Epi& E, const int tid_arg) {
;     ...
;         const bool has_next = S.next(ui + 1, nxt);
;         const char* nA = has_next ? (const char*)g.A + (size_t)nxt.pm * tstep : cA; const char* nB = has_next ? (const char*)g.Bt + (size_t)nxt.pn * tstep : cB;
;     ...
; #pragma unroll
;         for (int a = 0; a < 2; ++a)
; #pragma unroll
;             for (int b = 0; b < 2; ++b)
; #pragma unroll
;                 for (int m = 0; m < 4; ++m)
; #pragma unroll
;                     for (int n = 0; n < 2; ++n) acc[a][b][m][n] = (f32x4){0.f, 0.f, 0.f, 0.f};
.LBB0_1079:
	s_ashr_i32 s21, s20, 31
	s_lshl_b64 s[22:23], s[20:21], 19
	s_add_u32 s22, s0, s22
	s_addc_u32 s23, s1, s23
	s_and_b64 s[24:25], s[10:11], exec
	s_cselect_b32 s21, s23, s29
	s_cselect_b32 s47, s22, s28
	s_ashr_i32 s17, s16, 31
	s_lshl_b64 s[24:25], s[16:17], 19
	s_add_u32 s24, s2, s24
	s_addc_u32 s25, s3, s25
	s_and_b64 s[34:35], s[10:11], exec
	s_cselect_b32 s17, s25, s31
	s_cselect_b32 s48, s24, s30
	s_add_u32 s28, s28, 0x40080
	s_addc_u32 s29, s29, 0
	s_add_u32 s49, s30, 0x100
	v_mov_b32_e32 v2, 0
	s_addc_u32 s50, s31, 0
	s_mov_b32 s51, -2
	v_mov_b32_e32 v3, v2
	v_mov_b32_e32 v4, v2
	v_mov_b32_e32 v5, v2
	v_mov_b32_e32 v6, v2
	v_mov_b32_e32 v7, v2
	v_mov_b32_e32 v8, v2
	v_mov_b32_e32 v9, v2
	v_mov_b32_e32 v18, v2
	v_mov_b32_e32 v19, v2
	v_mov_b32_e32 v20, v2
	v_mov_b32_e32 v21, v2
	v_mov_b32_e32 v22, v2
	v_mov_b32_e32 v23, v2
	v_mov_b32_e32 v24, v2
	v_mov_b32_e32 v25, v2
	v_mov_b32_e32 v34, v2
	v_mov_b32_e32 v35, v2
	v_mov_b32_e32 v36, v2
	v_mov_b32_e32 v37, v2
	v_mov_b32_e32 v38, v2
	v_mov_b32_e32 v39, v2
	v_mov_b32_e32 v40, v2
	v_mov_b32_e32 v41, v2
	v_mov_b32_e32 v50, v2
	v_mov_b32_e32 v51, v2
	v_mov_b32_e32 v52, v2
	v_mov_b32_e32 v53, v2
	v_mov_b32_e32 v54, v2
	v_mov_b32_e32 v55, v2
	v_mov_b32_e32 v56, v2
	v_mov_b32_e32 v57, v2
	v_mov_b32_e32 v10, v2
	v_mov_b32_e32 v11, v2
	v_mov_b32_e32 v12, v2
	v_mov_b32_e32 v13, v2
	v_mov_b32_e32 v14, v2
	v_mov_b32_e32 v15, v2
	v_mov_b32_e32 v16, v2
	v_mov_b32_e32 v17, v2
	v_mov_b32_e32 v26, v2
	v_mov_b32_e32 v27, v2
	v_mov_b32_e32 v28, v2
	v_mov_b32_e32 v29, v2
	v_mov_b32_e32 v30, v2
	v_mov_b32_e32 v31, v2
	v_mov_b32_e32 v32, v2
	v_mov_b32_e32 v33, v2
	v_mov_b32_e32 v42, v2
	v_mov_b32_e32 v43, v2
	v_mov_b32_e32 v44, v2
	v_mov_b32_e32 v45, v2
	v_mov_b32_e32 v46, v2
	v_mov_b32_e32 v47, v2
	v_mov_b32_e32 v48, v2
	v_mov_b32_e32 v49, v2
	v_mov_b32_e32 v58, v2
	v_mov_b32_e32 v59, v2
	v_mov_b32_e32 v60, v2
	v_mov_b32_e32 v61, v2
	v_mov_b32_e32 v62, v2
	v_mov_b32_e32 v63, v2
	v_mov_b32_e32 v64, v2
	v_mov_b32_e32 v65, v2
	v_mov_b32_e32 v66, v2
	v_mov_b32_e32 v67, v2
	v_mov_b32_e32 v68, v2
	v_mov_b32_e32 v69, v2
	v_mov_b32_e32 v70, v2
	v_mov_b32_e32 v71, v2
	v_mov_b32_e32 v72, v2
	v_mov_b32_e32 v73, v2
	v_mov_b32_e32 v82, v2
	v_mov_b32_e32 v83, v2
	v_mov_b32_e32 v84, v2
	v_mov_b32_e32 v85, v2
	v_mov_b32_e32 v86, v2
	v_mov_b32_e32 v87, v2
	v_mov_b32_e32 v88, v2
	v_mov_b32_e32 v89, v2
	v_mov_b32_e32 v98, v2
	v_mov_b32_e32 v99, v2
	v_mov_b32_e32 v100, v2
	v_mov_b32_e32 v101, v2
	v_mov_b32_e32 v102, v2
	v_mov_b32_e32 v103, v2
	v_mov_b32_e32 v104, v2
	v_mov_b32_e32 v105, v2
	v_mov_b32_e32 v114, v2
	v_mov_b32_e32 v115, v2
	v_mov_b32_e32 v116, v2
	v_mov_b32_e32 v117, v2
	v_mov_b32_e32 v118, v2
	v_mov_b32_e32 v119, v2
	v_mov_b32_e32 v120, v2
	v_mov_b32_e32 v121, v2
	v_mov_b32_e32 v74, v2
	v_mov_b32_e32 v75, v2
	v_mov_b32_e32 v76, v2
	v_mov_b32_e32 v77, v2
	v_mov_b32_e32 v78, v2
	v_mov_b32_e32 v79, v2
	v_mov_b32_e32 v80, v2
	v_mov_b32_e32 v81, v2
	v_mov_b32_e32 v90, v2
	v_mov_b32_e32 v91, v2
	v_mov_b32_e32 v92, v2
	v_mov_b32_e32 v93, v2
	v_mov_b32_e32 v94, v2
	v_mov_b32_e32 v95, v2
	v_mov_b32_e32 v96, v2
	v_mov_b32_e32 v97, v2
	v_mov_b32_e32 v106, v2
	v_mov_b32_e32 v107, v2
	v_mov_b32_e32 v108, v2
	v_mov_b32_e32 v109, v2
	v_mov_b32_e32 v110, v2
	v_mov_b32_e32 v111, v2
	v_mov_b32_e32 v112, v2
	v_mov_b32_e32 v113, v2
	v_mov_b32_e32 v122, v2
	v_mov_b32_e32 v123, v2
	v_mov_b32_e32 v124, v2
	v_mov_b32_e32 v125, v2
	v_mov_b32_e32 v126, v2
	v_mov_b32_e32 v127, v2
	v_mov_b32_e32 v128, v2
	v_mov_b32_e32 v129, v2
	s_nop 0
	s_nop 0
	s_nop 0
	s_nop 0
	s_nop 0
	s_nop 0
	s_nop 0
	s_nop 0
	s_nop 0
	s_nop 0
	s_nop 0

; __device__ __forceinline__ unsigned xb_ld(unsigned* p)              { return __hip_atomic_load(p, __ATOMIC_RELAXED, __HIP_MEMORY_SCOPE_AGENT); }
; __device__ __forceinline__ unsigned xb_add(unsigned* p, unsigned v) { return __hip_atomic_fetch_add(p, v, __ATOMIC_RELAXED, __HIP_MEMORY_SCOPE_AGENT); }
; #define XB_SPIN(cond, bar) do { unsigned _sp = 0; while (cond) { __builtin_amdgcn_s_sleep(1); \
;     if ((++_sp & 255u) == 0u) { if (xb_ld(&(bar)[XB_TMO])) break; if (_sp > XB_SPIN_CAP) { atomicAdd(&(bar)[XB_TMO], 1u); break; } } } } while (0)
; __device__ __forceinline__ void xcd_barrier(const XcdBarrier& b, const bool leader) {
;     ...
;         const unsigned old = xb_add(&bar[XB_XSUB(b.x)], 1u);
;         const unsigned gen = old / nloc;
;         if (old + 1u == (gen + 1u) * nloc) {
;             __builtin_amdgcn_fence(__ATOMIC_RELEASE, "agent");
;             asm volatile("s_waitcnt vmcnt(0)" ::: "memory");
;             const unsigned og = xb_add(&bar[XB_TOP], 1u);
;             const unsigned tg = og / nx;
;             if (og + 1u == (tg + 1u) * nx) xb_add(&bar[XB_TOPGEN], 1u);
;             else XB_SPIN(xb_ld(&bar[XB_TOPGEN]) == tg, bar);
;             __builtin_amdgcn_fence(__ATOMIC_ACQUIRE, "agent");
;             xb_add(&bar[XB_XGEN(b.x)], 1u);
;             asm volatile("s_waitcnt vmcnt(0)" ::: "memory");
;         } else {
;             XB_SPIN(xb_ld(&bar[XB_XGEN(b.x)]) == gen, bar);
.LBB0_1115:
	s_or_b64 exec, exec, s[12:13]
	v_cvt_f32_u32_e32 v4, v2
	s_waitcnt vmcnt(0)
	v_readfirstlane_b32 s0, v3
	v_sub_u32_e32 v3, 0, v2
	v_rcp_iflag_f32_e32 v4, v4
	v_add_u32_e32 v5, s0, v1
	v_mul_f32_e32 v4, 0x4f7ffffe, v4
	v_cvt_u32_f32_e32 v4, v4
	v_mul_lo_u32 v1, v3, v4
	v_mul_hi_u32 v1, v4, v1
	v_add_u32_e32 v1, v4, v1
	v_mul_hi_u32 v1, v5, v1
	v_mul_lo_u32 v3, v1, v2
	v_sub_u32_e32 v3, v5, v3
	v_add_u32_e32 v4, 1, v1
	v_cmp_ge_u32_e32 vcc, v3, v2
	s_nop 1
	v_cndmask_b32_e32 v1, v1, v4, vcc
	v_sub_u32_e32 v4, v3, v2
	v_cndmask_b32_e32 v3, v3, v4, vcc
	v_add_u32_e32 v4, 1, v1
	v_cmp_ge_u32_e32 vcc, v3, v2
	v_add_u32_e32 v3, 1, v5
	s_nop 0
	v_cndmask_b32_e32 v1, v1, v4, vcc
	v_mul_lo_u32 v4, v2, v1
	v_add_u32_e32 v2, v4, v2
	v_add_u32_e32 v4, 1, v4
	v_cmp_eq_u32_e32 vcc, v3, v4
	s_cbranch_vccz .Lewb_9
	buffer_wbl2 sc1
.Lewb_9:
	v_cmp_ne_u32_e32 vcc, v3, v2
	s_and_saveexec_b64 s[0:1], vcc
	s_xor_b64 s[10:11], exec, s[0:1]
	s_cbranch_execz .LBB0_1129
	s_waitcnt lgkmcnt(0)
	v_mov_b32_e32 v0, 0x2000
	s_load_dwordx2 s[16:17], s[90:91], 0xb0
	s_waitcnt lgkmcnt(0)
	s_add_u32 s16, s16, 0x1d79b500
	s_addc_u32 s17, s17, 0
	v_mov_b32_e32 v0, 0
	global_load_dword v0, v0, s[16:17] sc1
	s_waitcnt vmcnt(0)
	v_cmp_eq_u32_e32 vcc, v0, v1
	s_and_saveexec_b64 s[12:13], vcc
	s_cbranch_execz .LBB0_1128
	s_add_u32 s14, s18, 0x1d798200
	s_addc_u32 s15, s19, 0
	s_mov_b32 s0, 1
	s_mov_b64 s[20:21], 0
	v_mov_b32_e32 v0, 0
	s_branch .LBB0_1119

; #define PG8_STAGE(bufoff, gbase, voff) do { _Pragma("unroll") for (int _i = 0; _i < 2; ++_i) \
;         __builtin_amdgcn_global_load_lds((const unsigned*)((const char*)(gbase) + (voff)[_i]), (PG8_LAS unsigned*)(lds + (bufoff) + ldsw + _i * 8192), 16, 0, 0); } while (0)
; #define PG8_LDA(dst, b, h) do { _Pragma("unroll") for (int m = 0; m < 4; ++m) _Pragma("unroll") for (int k = 0; k < 2; ++k) dst[m][k] = *(const PG8_LAS bf16x8*)(lds + PG8_SA(b, h) + aoff + m * 2048 + k * 1024); } while (0)
; #define PG8_LDB(dst, b, h) do { _Pragma("unroll") for (int n = 0; n < 2; ++n) _Pragma("unroll") for (int k = 0; k < 2; ++k) dst[n][k] = *(const PG8_LAS bf16x8*)(lds + PG8_SB(b, h) + boff + n * 2048 + k * 1024); } while (0)
; #define PG8_MMA(ai, bj, At, Bt) do { __builtin_amdgcn_s_setprio(1); _Pragma("unroll") for (int m = 0; m < 4; ++m) _Pragma("unroll") for (int n = 0; n < 2; ++n) _Pragma("unroll") for (int k = 0; k < 2; ++k) \
;         acc[ai][bj][m][n] = __builtin_amdgcn_mfma_f32_16x16x32_bf16(Bt[n][k], At[m][k], acc[ai][bj][m][n], 0, 0, 0); __builtin_amdgcn_s_setprio(0); } while (0)
; #define PG8_WAIT_V(n) asm volatile("s_waitcnt vmcnt(" #n ")" ::: "memory")
; template <class Epi, class Sched, bool ALIGN_EPI = false, bool SP2 = false>
; __device__ __forceinline__ void gemm_phase(PG8_LAS unsigned char* lds, const Gemm g, const Sched& S, const Epi& E, const int tid_arg) {
;     ...
;         for (int t = 0; t < nt; t += 2) {
;             const bool last = (t == nt - 2);
;             const char* a1 = cA + (size_t)(t + 1) * kstep;
;             const char* a2 = last ? nA : cA + (size_t)(t + 2) * kstep; const char* b2 = last ? nB : cB + (size_t)(t + 2) * kstep;
;             const char* a3 = a2 + kstep; const char* b3 = b2 + kstep;
;             if (last && has_next) S.a_ready(nxt);
;             if constexpr (SP2) {
;             PG8_LDB(B0, 0, 0); PG8_LDB(B1, 0, 1); PG8_SCHED; PG8_LDA(At, 0, 0); PG8_STAGE(PG8_SA(1, 1), a1 + hstep, voffA);
;             PG8_WAIT_V(8); PG8_WAIT_L(0); PG8_BAR; PG8_MMA(0, 0, At, B0); PG8_MMA(0, 1, At, B1); PG8_BAR; PG8_SCHED;
;     ...
; #pragma unroll
;         for (int a = 0; a < 2; ++a)
; #pragma unroll
;             for (int b = 0; b < 2; ++b)
; #pragma unroll
;                 for (int m = 0; m < 4; ++m)
; #pragma unroll
;                     for (int n = 0; n < 2; ++n) acc[a][b][m][n] = (f32x4){0.f, 0.f, 0.f, 0.f};
.LBB0_1169:
	s_add_u32 s23, s26, 0x100
	v_mov_b32_e32 v0, 0
	s_addc_u32 s46, s27, 0
	s_mov_b32 s47, -2
	v_mov_b32_e32 v1, v0
	v_mov_b32_e32 v2, v0
	v_mov_b32_e32 v3, v0
	v_mov_b32_e32 v4, v0
	v_mov_b32_e32 v5, v0
	v_mov_b32_e32 v6, v0
	v_mov_b32_e32 v7, v0
	v_mov_b32_e32 v16, v0
	v_mov_b32_e32 v17, v0
	v_mov_b32_e32 v18, v0
	v_mov_b32_e32 v19, v0
	v_mov_b32_e32 v20, v0
	v_mov_b32_e32 v21, v0
	v_mov_b32_e32 v22, v0
	v_mov_b32_e32 v23, v0
	v_mov_b32_e32 v32, v0
	v_mov_b32_e32 v33, v0
	v_mov_b32_e32 v34, v0
	v_mov_b32_e32 v35, v0
	v_mov_b32_e32 v36, v0
	v_mov_b32_e32 v37, v0
	v_mov_b32_e32 v38, v0
	v_mov_b32_e32 v39, v0
	v_mov_b32_e32 v48, v0
	v_mov_b32_e32 v49, v0
	v_mov_b32_e32 v50, v0
	v_mov_b32_e32 v51, v0
	v_mov_b32_e32 v52, v0
	v_mov_b32_e32 v53, v0
	v_mov_b32_e32 v54, v0
	v_mov_b32_e32 v55, v0
	v_mov_b32_e32 v8, v0
	v_mov_b32_e32 v9, v0
	v_mov_b32_e32 v10, v0
	v_mov_b32_e32 v11, v0
	v_mov_b32_e32 v12, v0
	v_mov_b32_e32 v13, v0
	v_mov_b32_e32 v14, v0
	v_mov_b32_e32 v15, v0
	v_mov_b32_e32 v24, v0
	v_mov_b32_e32 v25, v0
	v_mov_b32_e32 v26, v0
	v_mov_b32_e32 v27, v0
	v_mov_b32_e32 v28, v0
	v_mov_b32_e32 v29, v0
	v_mov_b32_e32 v30, v0
	v_mov_b32_e32 v31, v0
	v_mov_b32_e32 v40, v0
	v_mov_b32_e32 v41, v0
	v_mov_b32_e32 v42, v0
	v_mov_b32_e32 v43, v0
	v_mov_b32_e32 v44, v0
	v_mov_b32_e32 v45, v0
	v_mov_b32_e32 v46, v0
	v_mov_b32_e32 v47, v0
	v_mov_b32_e32 v56, v0
	v_mov_b32_e32 v57, v0
	v_mov_b32_e32 v58, v0
	v_mov_b32_e32 v59, v0
	v_mov_b32_e32 v60, v0
	v_mov_b32_e32 v61, v0
	v_mov_b32_e32 v62, v0
	v_mov_b32_e32 v63, v0
	v_mov_b32_e32 v64, v0
	v_mov_b32_e32 v65, v0
	v_mov_b32_e32 v66, v0
	v_mov_b32_e32 v67, v0
	v_mov_b32_e32 v68, v0
	v_mov_b32_e32 v69, v0
	v_mov_b32_e32 v70, v0
	v_mov_b32_e32 v71, v0
	v_mov_b32_e32 v80, v0
	v_mov_b32_e32 v81, v0
	v_mov_b32_e32 v82, v0
	v_mov_b32_e32 v83, v0
	v_mov_b32_e32 v84, v0
	v_mov_b32_e32 v85, v0
	v_mov_b32_e32 v86, v0
	v_mov_b32_e32 v87, v0
	v_mov_b32_e32 v96, v0
	v_mov_b32_e32 v97, v0
	v_mov_b32_e32 v98, v0
	v_mov_b32_e32 v99, v0
	v_mov_b32_e32 v100, v0
	v_mov_b32_e32 v101, v0
	v_mov_b32_e32 v102, v0
	v_mov_b32_e32 v103, v0
	v_mov_b32_e32 v112, v0
	v_mov_b32_e32 v113, v0
	v_mov_b32_e32 v114, v0
	v_mov_b32_e32 v115, v0
	v_mov_b32_e32 v116, v0
	v_mov_b32_e32 v117, v0
	v_mov_b32_e32 v118, v0
	v_mov_b32_e32 v119, v0
	v_mov_b32_e32 v72, v0
	v_mov_b32_e32 v73, v0
	v_mov_b32_e32 v74, v0
	v_mov_b32_e32 v75, v0
	v_mov_b32_e32 v76, v0
	v_mov_b32_e32 v77, v0
	v_mov_b32_e32 v78, v0
	v_mov_b32_e32 v79, v0
	v_mov_b32_e32 v88, v0
	v_mov_b32_e32 v89, v0
	v_mov_b32_e32 v90, v0
	v_mov_b32_e32 v91, v0
	v_mov_b32_e32 v92, v0
	v_mov_b32_e32 v93, v0
	v_mov_b32_e32 v94, v0
	v_mov_b32_e32 v95, v0
	v_mov_b32_e32 v104, v0
	v_mov_b32_e32 v105, v0
	v_mov_b32_e32 v106, v0
	v_mov_b32_e32 v107, v0
	v_mov_b32_e32 v108, v0
	v_mov_b32_e32 v109, v0
	v_mov_b32_e32 v110, v0
	v_mov_b32_e32 v111, v0
	v_mov_b32_e32 v120, v0
	v_mov_b32_e32 v121, v0
	v_mov_b32_e32 v122, v0
	v_mov_b32_e32 v123, v0
	v_mov_b32_e32 v124, v0
	v_mov_b32_e32 v125, v0
	v_mov_b32_e32 v126, v0
	v_mov_b32_e32 v127, v0
	s_nop 0
	s_nop 0
	s_nop 0
	s_nop 0
	s_nop 0
	s_nop 0
	s_nop 0
	s_nop 0
	s_nop 0
	s_nop 0
	s_nop 0
	s_nop 0
	s_nop 0
	s_nop 0
	s_nop 0
	s_nop 0
	s_nop 0
	s_nop 0
	s_nop 0
	s_nop 0
	s_nop 0
.LBB0_1170:
	ds_read_b128 v[160:163], v156
	ds_read_b128 v[164:167], v156 offset:1024
	ds_read_b128 v[168:171], v156 offset:2048
	ds_read_b128 v[172:175], v156 offset:3072
	ds_read_b128 v[176:179], v157
	ds_read_b128 v[182:185], v157 offset:1024
	ds_read_b128 v[186:189], v157 offset:2048
	ds_read_b128 v[190:193], v157 offset:3072
	s_add_u32 s26, s24, 0x100
	s_addc_u32 s27, s25, 0
	s_cmp_eq_u32 s47, 40
	s_cselect_b32 s31, s11, s27
	s_cselect_b32 s30, s10, s26
	s_cselect_b32 s29, s21, s46
	s_cselect_b32 s28, s20, s23
	v_lshl_add_u64 v[144:145], s[24:25], 0, v[136:137]
	s_add_i32 m0, s34, 0xc000
	ds_read_b128 v[202:205], v158
	ds_read_b128 v[206:209], v158 offset:1024
	ds_read_b128 v[210:213], v158 offset:2048
	ds_read_b128 v[214:217], v158 offset:3072
	ds_read_b128 v[218:221], v158 offset:4096
	ds_read_b128 v[222:225], v158 offset:5120
	ds_read_b128 v[226:229], v158 offset:6144
	ds_read_b128 v[230:233], v158 offset:7168
	global_load_lds_dwordx4 v[144:145], off
	v_lshl_add_u64 v[144:145], s[24:25], 0, v[138:139]
	s_add_i32 m0, s34, 0xe000
	s_nop 0
	global_load_lds_dwordx4 v[144:145], off
	s_waitcnt vmcnt(8)
	s_waitcnt lgkmcnt(0)
	s_barrier
	s_setprio 1
	s_waitcnt lgkmcnt(0)
	v_mfma_f32_16x16x32_bf16 v[124:127], v[160:163], v[202:205], v[124:127]
	v_mfma_f32_16x16x32_bf16 v[120:123], v[168:171], v[202:205], v[120:123]
	v_mfma_f32_16x16x32_bf16 v[108:111], v[160:163], v[210:213], v[108:111]
	v_mfma_f32_16x16x32_bf16 v[104:107], v[168:171], v[210:213], v[104:107]
	v_mfma_f32_16x16x32_bf16 v[92:95], v[160:163], v[218:221], v[92:95]
	v_mfma_f32_16x16x32_bf16 v[88:91], v[168:171], v[218:221], v[88:91]
	v_mfma_f32_16x16x32_bf16 v[76:79], v[160:163], v[226:229], v[76:79]
	v_mfma_f32_16x16x32_bf16 v[72:75], v[168:171], v[226:229], v[72:75]
	v_mfma_f32_16x16x32_bf16 v[124:127], v[164:167], v[206:209], v[124:127]
	v_mfma_f32_16x16x32_bf16 v[120:123], v[172:175], v[206:209], v[120:123]
	v_mfma_f32_16x16x32_bf16 v[108:111], v[164:167], v[214:217], v[108:111]
	v_mfma_f32_16x16x32_bf16 v[104:107], v[172:175], v[214:217], v[104:107]
	v_mfma_f32_16x16x32_bf16 v[92:95], v[164:167], v[222:225], v[92:95]
	v_mfma_f32_16x16x32_bf16 v[88:91], v[172:175], v[222:225], v[88:91]
	v_mfma_f32_16x16x32_bf16 v[76:79], v[164:167], v[230:233], v[76:79]
	v_mfma_f32_16x16x32_bf16 v[72:75], v[172:175], v[230:233], v[72:75]
	s_setprio 0
	s_setprio 1
	v_mfma_f32_16x16x32_bf16 v[116:119], v[176:179], v[202:205], v[116:119]
	v_mfma_f32_16x16x32_bf16 v[112:115], v[186:189], v[202:205], v[112:115]
	v_mfma_f32_16x16x32_bf16 v[100:103], v[176:179], v[210:213], v[100:103]
	v_mfma_f32_16x16x32_bf16 v[96:99], v[186:189], v[210:213], v[96:99]
	v_mfma_f32_16x16x32_bf16 v[84:87], v[176:179], v[218:221], v[84:87]
	v_mfma_f32_16x16x32_bf16 v[80:83], v[186:189], v[218:221], v[80:83]
	v_mfma_f32_16x16x32_bf16 v[68:71], v[176:179], v[226:229], v[68:71]
	v_mfma_f32_16x16x32_bf16 v[64:67], v[186:189], v[226:229], v[64:67]
	v_mfma_f32_16x16x32_bf16 v[116:119], v[182:185], v[206:209], v[116:119]
	v_mfma_f32_16x16x32_bf16 v[112:115], v[190:193], v[206:209], v[112:115]
	v_mfma_f32_16x16x32_bf16 v[100:103], v[182:185], v[214:217], v[100:103]
	v_mfma_f32_16x16x32_bf16 v[96:99], v[190:193], v[214:217], v[96:99]
	v_mfma_f32_16x16x32_bf16 v[84:87], v[182:185], v[222:225], v[84:87]
	v_mfma_f32_16x16x32_bf16 v[80:83], v[190:193], v[222:225], v[80:83]
	v_mfma_f32_16x16x32_bf16 v[68:71], v[182:185], v[230:233], v[68:71]
	v_mfma_f32_16x16x32_bf16 v[64:67], v[190:193], v[230:233], v[64:67]
	s_setprio 0
	s_barrier
; #define PG8_STAGE(bufoff, gbase, voff) do { _Pragma("unroll") for (int _i = 0; _i < 2; ++_i) \
;         __builtin_amdgcn_global_load_lds((const unsigned*)((const char*)(gbase) + (voff)[_i]), (PG8_LAS unsigned*)(lds + (bufoff) + ldsw + _i * 8192), 16, 0, 0); } while (0)
; #define PG8_LDA(dst, b, h) do { _Pragma("unroll") for (int m = 0; m < 4; ++m) _Pragma("unroll") for (int k = 0; k < 2; ++k) dst[m][k] = *(const PG8_LAS bf16x8*)(lds + PG8_SA(b, h) + aoff + m * 2048 + k * 1024); } while (0)
; #define PG8_LDB(dst, b, h) do { _Pragma("unroll") for (int n = 0; n < 2; ++n) _Pragma("unroll") for (int k = 0; k < 2; ++k) dst[n][k] = *(const PG8_LAS bf16x8*)(lds + PG8_SB(b, h) + boff + n * 2048 + k * 1024); } while (0)
; #define PG8_MMA(ai, bj, At, Bt) do { __builtin_amdgcn_s_setprio(1); _Pragma("unroll") for (int m = 0; m < 4; ++m) _Pragma("unroll") for (int n = 0; n < 2; ++n) _Pragma("unroll") for (int k = 0; k < 2; ++k) \
;         acc[ai][bj][m][n] = __builtin_amdgcn_mfma_f32_16x16x32_bf16(Bt[n][k], At[m][k], acc[ai][bj][m][n], 0, 0, 0); __builtin_amdgcn_s_setprio(0); } while (0)
; #define PG8_WAIT_V(n) asm volatile("s_waitcnt vmcnt(" #n ")" ::: "memory")
; #define PG8_WAIT_L(n) asm volatile("s_waitcnt lgkmcnt(" #n ")" ::: "memory")
; #define PG8_BAR __builtin_amdgcn_s_barrier()
; #define PG8_SCHED __builtin_amdgcn_sched_barrier(0)
; template <class Epi, class Sched, bool ALIGN_EPI = false, bool SP2 = false>
; __device__ __forceinline__ void gemm_phase(PG8_LAS unsigned char* lds, const Gemm g, const Sched& S, const Epi& E, const int tid_arg) {
;     ...
;             PG8_LDA(At, 0, 1); PG8_STAGE(PG8_SB(0, 0), b2, voffB); PG8_STAGE(PG8_SB(0, 1), b2 + hstep, voffB); PG8_STAGE(PG8_SA(0, 0), a2, voffA);
;             PG8_WAIT_V(8); PG8_WAIT_L(0); PG8_BAR; PG8_MMA(1, 0, At, B0); PG8_MMA(1, 1, At, B1); PG8_BAR; PG8_SCHED;
;             PG8_LDB(B0, 1, 0); PG8_LDB(B1, 1, 1); PG8_SCHED; PG8_LDA(At, 1, 0); PG8_STAGE(PG8_SA(0, 1), a2 + hstep, voffA);
;             PG8_WAIT_V(8); PG8_WAIT_L(0); PG8_BAR; PG8_MMA(0, 0, At, B0); PG8_MMA(0, 1, At, B1); PG8_BAR; PG8_SCHED;
	s_add_i32 s24, s41, s33
	v_lshl_add_u64 v[144:145], s[28:29], 0, v[130:131]
	s_mov_b32 m0, s24
	ds_read_b128 v[202:205], v158 offset:16384
	ds_read_b128 v[206:209], v158 offset:17408
	ds_read_b128 v[210:213], v158 offset:18432
	ds_read_b128 v[214:217], v158 offset:19456
	ds_read_b128 v[218:221], v158 offset:20480
	ds_read_b128 v[222:225], v158 offset:21504
	ds_read_b128 v[226:229], v158 offset:22528
	ds_read_b128 v[230:233], v158 offset:23552
	global_load_lds_dwordx4 v[144:145], off
	s_add_i32 m0, s24, 0x2000
	s_add_u32 s24, s28, 0xb0000
	v_lshl_add_u64 v[194:195], s[28:29], 0, v[134:135]
	s_addc_u32 s25, s29, 0
	s_add_i32 s48, s42, s33
	global_load_lds_dwordx4 v[194:195], off
	v_lshl_add_u64 v[234:235], s[24:25], 0, v[130:131]
	s_mov_b32 m0, s48
	v_lshl_add_u64 v[236:237], s[30:31], 0, v[132:133]
	global_load_lds_dwordx4 v[234:235], off
	v_lshl_add_u64 v[234:235], s[24:25], 0, v[134:135]
	s_add_i32 m0, s48, 0x2000
	s_nop 0
	global_load_lds_dwordx4 v[234:235], off
	v_lshl_add_u64 v[234:235], s[30:31], 0, v[128:129]
	s_mov_b32 m0, s34
	s_nop 0
	global_load_lds_dwordx4 v[234:235], off
	s_mov_b32 m0, s35
	s_nop 0
	global_load_lds_dwordx4 v[236:237], off
	s_waitcnt vmcnt(8)
	s_waitcnt lgkmcnt(0)
	s_barrier
	s_setprio 1
	s_waitcnt lgkmcnt(0)
	v_mfma_f32_16x16x32_bf16 v[60:63], v[160:163], v[202:205], v[60:63]
	v_mfma_f32_16x16x32_bf16 v[56:59], v[168:171], v[202:205], v[56:59]
	v_mfma_f32_16x16x32_bf16 v[44:47], v[160:163], v[210:213], v[44:47]
	v_mfma_f32_16x16x32_bf16 v[40:43], v[168:171], v[210:213], v[40:43]
	v_mfma_f32_16x16x32_bf16 v[28:31], v[160:163], v[218:221], v[28:31]
	v_mfma_f32_16x16x32_bf16 v[24:27], v[168:171], v[218:221], v[24:27]
	v_mfma_f32_16x16x32_bf16 v[12:15], v[160:163], v[226:229], v[12:15]
	v_mfma_f32_16x16x32_bf16 v[8:11], v[168:171], v[226:229], v[8:11]
	v_mfma_f32_16x16x32_bf16 v[60:63], v[164:167], v[206:209], v[60:63]
	v_mfma_f32_16x16x32_bf16 v[56:59], v[172:175], v[206:209], v[56:59]
	v_mfma_f32_16x16x32_bf16 v[44:47], v[164:167], v[214:217], v[44:47]
	v_mfma_f32_16x16x32_bf16 v[40:43], v[172:175], v[214:217], v[40:43]
	v_mfma_f32_16x16x32_bf16 v[28:31], v[164:167], v[222:225], v[28:31]
	v_mfma_f32_16x16x32_bf16 v[24:27], v[172:175], v[222:225], v[24:27]
	v_mfma_f32_16x16x32_bf16 v[12:15], v[164:167], v[230:233], v[12:15]
	v_mfma_f32_16x16x32_bf16 v[8:11], v[172:175], v[230:233], v[8:11]
	s_setprio 0
	s_setprio 1
	v_mfma_f32_16x16x32_bf16 v[52:55], v[176:179], v[202:205], v[52:55]
	v_mfma_f32_16x16x32_bf16 v[48:51], v[186:189], v[202:205], v[48:51]
	v_mfma_f32_16x16x32_bf16 v[36:39], v[176:179], v[210:213], v[36:39]
	v_mfma_f32_16x16x32_bf16 v[32:35], v[186:189], v[210:213], v[32:35]
	v_mfma_f32_16x16x32_bf16 v[20:23], v[176:179], v[218:221], v[20:23]
	v_mfma_f32_16x16x32_bf16 v[16:19], v[186:189], v[218:221], v[16:19]
	v_mfma_f32_16x16x32_bf16 v[4:7], v[176:179], v[226:229], v[4:7]
	v_mfma_f32_16x16x32_bf16 v[0:3], v[186:189], v[226:229], v[0:3]
	v_mfma_f32_16x16x32_bf16 v[52:55], v[182:185], v[206:209], v[52:55]
	v_mfma_f32_16x16x32_bf16 v[48:51], v[190:193], v[206:209], v[48:51]
	v_mfma_f32_16x16x32_bf16 v[36:39], v[182:185], v[214:217], v[36:39]
	v_mfma_f32_16x16x32_bf16 v[32:35], v[190:193], v[214:217], v[32:35]
	v_mfma_f32_16x16x32_bf16 v[20:23], v[182:185], v[222:225], v[20:23]
	v_mfma_f32_16x16x32_bf16 v[16:19], v[190:193], v[222:225], v[16:19]
	v_mfma_f32_16x16x32_bf16 v[4:7], v[182:185], v[230:233], v[4:7]
	v_mfma_f32_16x16x32_bf16 v[0:3], v[190:193], v[230:233], v[0:3]
	s_setprio 0
	s_barrier
	s_add_i32 s48, 0, 0x18000
	v_add_u32_e32 v159, s48, v147
	s_add_i32 s49, 0, 0x1c000
	ds_read_b128 v[160:163], v159
	ds_read_b128 v[164:167], v159 offset:1024
	ds_read_b128 v[168:171], v159 offset:2048
	ds_read_b128 v[172:175], v159 offset:3072
	v_add_u32_e32 v159, s49, v147
	ds_read_b128 v[176:179], v159
	ds_read_b128 v[182:185], v159 offset:1024
	ds_read_b128 v[186:189], v159 offset:2048
	ds_read_b128 v[190:193], v159 offset:3072
	s_add_u32 s24, s30, 0xb0000
	s_addc_u32 s25, s31, 0
	s_mov_b32 m0, s36
	v_lshl_add_u64 v[238:239], s[24:25], 0, v[128:129]
	ds_read_b128 v[202:205], v158 offset:32768
	ds_read_b128 v[206:209], v158 offset:33792
	ds_read_b128 v[210:213], v158 offset:34816
	ds_read_b128 v[214:217], v158 offset:35840
	ds_read_b128 v[218:221], v158 offset:36864
	ds_read_b128 v[222:225], v158 offset:37888
	ds_read_b128 v[226:229], v158 offset:38912
	ds_read_b128 v[230:233], v158 offset:39936
	global_load_lds_dwordx4 v[238:239], off
	v_lshl_add_u64 v[238:239], s[24:25], 0, v[132:133]
	s_mov_b32 m0, s37
	s_nop 0
	global_load_lds_dwordx4 v[238:239], off
	s_waitcnt vmcnt(8)
	s_waitcnt lgkmcnt(0)
	s_barrier
; #define PG8_STAGE(bufoff, gbase, voff) do { _Pragma("unroll") for (int _i = 0; _i < 2; ++_i) \
;         __builtin_amdgcn_global_load_lds((const unsigned*)((const char*)(gbase) + (voff)[_i]), (PG8_LAS unsigned*)(lds + (bufoff) + ldsw + _i * 8192), 16, 0, 0); } while (0)
; #define PG8_LDA(dst, b, h) do { _Pragma("unroll") for (int m = 0; m < 4; ++m) _Pragma("unroll") for (int k = 0; k < 2; ++k) dst[m][k] = *(const PG8_LAS bf16x8*)(lds + PG8_SA(b, h) + aoff + m * 2048 + k * 1024); } while (0)
; #define PG8_MMA(ai, bj, At, Bt) do { __builtin_amdgcn_s_setprio(1); _Pragma("unroll") for (int m = 0; m < 4; ++m) _Pragma("unroll") for (int n = 0; n < 2; ++n) _Pragma("unroll") for (int k = 0; k < 2; ++k) \
;         acc[ai][bj][m][n] = __builtin_amdgcn_mfma_f32_16x16x32_bf16(Bt[n][k], At[m][k], acc[ai][bj][m][n], 0, 0, 0); __builtin_amdgcn_s_setprio(0); } while (0)
; #define PG8_WAIT_V(n) asm volatile("s_waitcnt vmcnt(" #n ")" ::: "memory")
; #define PG8_WAIT_L(n) asm volatile("s_waitcnt lgkmcnt(" #n ")" ::: "memory")
; #define PG8_BAR __builtin_amdgcn_s_barrier()
; #define PG8_SCHED __builtin_amdgcn_sched_barrier(0)
; template <class Epi, class Sched, bool ALIGN_EPI = false, bool SP2 = false>
; __device__ __forceinline__ void gemm_phase(PG8_LAS unsigned char* lds, const Gemm g, const Sched& S, const Epi& E, const int tid_arg) {
;     ...
;             PG8_WAIT_V(8); PG8_WAIT_L(0); PG8_BAR; PG8_MMA(0, 0, At, B0); PG8_MMA(0, 1, At, B1); PG8_BAR; PG8_SCHED;
;             PG8_LDA(At, 1, 1); PG8_STAGE(PG8_SB(1, 0), b3, voffB); PG8_STAGE(PG8_SB(1, 1), b3 + hstep, voffB); PG8_STAGE(PG8_SA(1, 0), a3, voffA);
;             PG8_WAIT_V(8); PG8_WAIT_L(0); PG8_BAR; PG8_MMA(1, 0, At, B0); PG8_MMA(1, 1, At, B1); PG8_BAR; PG8_SCHED;
;     ...
;         if constexpr (ALIGN_EPI) { if (wr == 0) PG8_BAR; }
	s_setprio 1
	s_waitcnt lgkmcnt(0)
	v_mfma_f32_16x16x32_bf16 v[124:127], v[160:163], v[202:205], v[124:127]
	v_mfma_f32_16x16x32_bf16 v[120:123], v[168:171], v[202:205], v[120:123]
	v_mfma_f32_16x16x32_bf16 v[108:111], v[160:163], v[210:213], v[108:111]
	v_mfma_f32_16x16x32_bf16 v[104:107], v[168:171], v[210:213], v[104:107]
	v_mfma_f32_16x16x32_bf16 v[92:95], v[160:163], v[218:221], v[92:95]
	v_mfma_f32_16x16x32_bf16 v[88:91], v[168:171], v[218:221], v[88:91]
	v_mfma_f32_16x16x32_bf16 v[76:79], v[160:163], v[226:229], v[76:79]
	v_mfma_f32_16x16x32_bf16 v[72:75], v[168:171], v[226:229], v[72:75]
	v_mfma_f32_16x16x32_bf16 v[124:127], v[164:167], v[206:209], v[124:127]
	v_mfma_f32_16x16x32_bf16 v[120:123], v[172:175], v[206:209], v[120:123]
	v_mfma_f32_16x16x32_bf16 v[108:111], v[164:167], v[214:217], v[108:111]
	v_mfma_f32_16x16x32_bf16 v[104:107], v[172:175], v[214:217], v[104:107]
	v_mfma_f32_16x16x32_bf16 v[92:95], v[164:167], v[222:225], v[92:95]
	v_mfma_f32_16x16x32_bf16 v[88:91], v[172:175], v[222:225], v[88:91]
	v_mfma_f32_16x16x32_bf16 v[76:79], v[164:167], v[230:233], v[76:79]
	v_mfma_f32_16x16x32_bf16 v[72:75], v[172:175], v[230:233], v[72:75]
	s_setprio 0
	s_setprio 1
	v_mfma_f32_16x16x32_bf16 v[116:119], v[176:179], v[202:205], v[116:119]
	v_mfma_f32_16x16x32_bf16 v[112:115], v[186:189], v[202:205], v[112:115]
	v_mfma_f32_16x16x32_bf16 v[100:103], v[176:179], v[210:213], v[100:103]
	v_mfma_f32_16x16x32_bf16 v[96:99], v[186:189], v[210:213], v[96:99]
	v_mfma_f32_16x16x32_bf16 v[84:87], v[176:179], v[218:221], v[84:87]
	v_mfma_f32_16x16x32_bf16 v[80:83], v[186:189], v[218:221], v[80:83]
	v_mfma_f32_16x16x32_bf16 v[68:71], v[176:179], v[226:229], v[68:71]
	v_mfma_f32_16x16x32_bf16 v[64:67], v[186:189], v[226:229], v[64:67]
	v_mfma_f32_16x16x32_bf16 v[116:119], v[182:185], v[206:209], v[116:119]
	v_mfma_f32_16x16x32_bf16 v[112:115], v[190:193], v[206:209], v[112:115]
	v_mfma_f32_16x16x32_bf16 v[100:103], v[182:185], v[214:217], v[100:103]
	v_mfma_f32_16x16x32_bf16 v[96:99], v[190:193], v[214:217], v[96:99]
	v_mfma_f32_16x16x32_bf16 v[84:87], v[182:185], v[222:225], v[84:87]
	v_mfma_f32_16x16x32_bf16 v[80:83], v[190:193], v[222:225], v[80:83]
	v_mfma_f32_16x16x32_bf16 v[68:71], v[182:185], v[230:233], v[68:71]
	v_mfma_f32_16x16x32_bf16 v[64:67], v[190:193], v[230:233], v[64:67]
	s_setprio 0
	s_barrier
	s_add_i32 s24, s48, s33
	v_lshl_add_u64 v[144:145], v[144:145], 0, s[16:17]
	s_mov_b32 m0, s24
	ds_read_b128 v[202:205], v158 offset:49152
	ds_read_b128 v[206:209], v158 offset:50176
	ds_read_b128 v[210:213], v158 offset:51200
	ds_read_b128 v[214:217], v158 offset:52224
	ds_read_b128 v[218:221], v158 offset:53248
	ds_read_b128 v[222:225], v158 offset:54272
	ds_read_b128 v[226:229], v158 offset:55296
	ds_read_b128 v[230:233], v158 offset:56320
	global_load_lds_dwordx4 v[144:145], off
	s_add_i32 m0, s24, 0x2000
	s_add_u32 s24, s28, 0xb0080
	v_lshl_add_u64 v[144:145], v[194:195], 0, s[16:17]
	s_addc_u32 s25, s29, 0
	s_add_i32 s28, s49, s33
	global_load_lds_dwordx4 v[144:145], off
	v_lshl_add_u64 v[144:145], s[24:25], 0, v[130:131]
	s_mov_b32 m0, s28
	s_nop 0
	global_load_lds_dwordx4 v[144:145], off
	v_lshl_add_u64 v[144:145], s[24:25], 0, v[134:135]
	s_add_i32 m0, s28, 0x2000
	s_nop 0
	global_load_lds_dwordx4 v[144:145], off
	v_lshl_add_u64 v[144:145], v[234:235], 0, s[16:17]
	s_mov_b32 m0, s39
	s_nop 0
	global_load_lds_dwordx4 v[144:145], off
	v_lshl_add_u64 v[144:145], v[236:237], 0, s[16:17]
	s_mov_b32 m0, s40
	s_nop 0
	global_load_lds_dwordx4 v[144:145], off
	s_waitcnt vmcnt(8)
	s_waitcnt lgkmcnt(0)
	s_barrier
	s_setprio 1
	s_waitcnt lgkmcnt(0)
	v_mfma_f32_16x16x32_bf16 v[60:63], v[160:163], v[202:205], v[60:63]
	v_mfma_f32_16x16x32_bf16 v[56:59], v[168:171], v[202:205], v[56:59]
	v_mfma_f32_16x16x32_bf16 v[44:47], v[160:163], v[210:213], v[44:47]
	v_mfma_f32_16x16x32_bf16 v[40:43], v[168:171], v[210:213], v[40:43]
	v_mfma_f32_16x16x32_bf16 v[28:31], v[160:163], v[218:221], v[28:31]
	v_mfma_f32_16x16x32_bf16 v[24:27], v[168:171], v[218:221], v[24:27]
	v_mfma_f32_16x16x32_bf16 v[12:15], v[160:163], v[226:229], v[12:15]
	v_mfma_f32_16x16x32_bf16 v[8:11], v[168:171], v[226:229], v[8:11]
	v_mfma_f32_16x16x32_bf16 v[60:63], v[164:167], v[206:209], v[60:63]
	v_mfma_f32_16x16x32_bf16 v[56:59], v[172:175], v[206:209], v[56:59]
	v_mfma_f32_16x16x32_bf16 v[44:47], v[164:167], v[214:217], v[44:47]
	v_mfma_f32_16x16x32_bf16 v[40:43], v[172:175], v[214:217], v[40:43]
	v_mfma_f32_16x16x32_bf16 v[28:31], v[164:167], v[222:225], v[28:31]
	v_mfma_f32_16x16x32_bf16 v[24:27], v[172:175], v[222:225], v[24:27]
	v_mfma_f32_16x16x32_bf16 v[12:15], v[164:167], v[230:233], v[12:15]
	v_mfma_f32_16x16x32_bf16 v[8:11], v[172:175], v[230:233], v[8:11]
	s_setprio 0
	s_setprio 1
	v_mfma_f32_16x16x32_bf16 v[52:55], v[176:179], v[202:205], v[52:55]
	v_mfma_f32_16x16x32_bf16 v[48:51], v[186:189], v[202:205], v[48:51]
	v_mfma_f32_16x16x32_bf16 v[36:39], v[176:179], v[210:213], v[36:39]
	v_mfma_f32_16x16x32_bf16 v[32:35], v[186:189], v[210:213], v[32:35]
	v_mfma_f32_16x16x32_bf16 v[20:23], v[176:179], v[218:221], v[20:23]
	v_mfma_f32_16x16x32_bf16 v[16:19], v[186:189], v[218:221], v[16:19]
	v_mfma_f32_16x16x32_bf16 v[4:7], v[176:179], v[226:229], v[4:7]
	v_mfma_f32_16x16x32_bf16 v[0:3], v[186:189], v[226:229], v[0:3]
	v_mfma_f32_16x16x32_bf16 v[52:55], v[182:185], v[206:209], v[52:55]
	v_mfma_f32_16x16x32_bf16 v[48:51], v[190:193], v[206:209], v[48:51]
	v_mfma_f32_16x16x32_bf16 v[36:39], v[182:185], v[214:217], v[36:39]
	v_mfma_f32_16x16x32_bf16 v[32:35], v[190:193], v[214:217], v[32:35]
	v_mfma_f32_16x16x32_bf16 v[20:23], v[182:185], v[222:225], v[20:23]
	v_mfma_f32_16x16x32_bf16 v[16:19], v[190:193], v[222:225], v[16:19]
	v_mfma_f32_16x16x32_bf16 v[4:7], v[182:185], v[230:233], v[4:7]
	v_mfma_f32_16x16x32_bf16 v[0:3], v[190:193], v[230:233], v[0:3]
	s_setprio 0
	s_barrier
	s_add_i32 s47, s47, 2
	s_add_u32 s23, s23, 0x100
	s_addc_u32 s46, s46, 0
	s_cmp_gt_u32 s47, 41
	s_mov_b64 s[24:25], s[26:27]
	s_cbranch_scc0 .LBB0_1170
	s_and_b64 vcc, exec, s[18:19]
	s_cbranch_vccz .LBB0_1173
	s_barrier

; __device__ __forceinline__ unsigned xb_ld(unsigned* p)              { return __hip_atomic_load(p, __ATOMIC_RELAXED, __HIP_MEMORY_SCOPE_AGENT); }
; __device__ __forceinline__ unsigned xb_add(unsigned* p, unsigned v) { return __hip_atomic_fetch_add(p, v, __ATOMIC_RELAXED, __HIP_MEMORY_SCOPE_AGENT); }
; #define XB_SPIN(cond, bar) do { unsigned _sp = 0; while (cond) { __builtin_amdgcn_s_sleep(1); \
;     if ((++_sp & 255u) == 0u) { if (xb_ld(&(bar)[XB_TMO])) break; if (_sp > XB_SPIN_CAP) { atomicAdd(&(bar)[XB_TMO], 1u); break; } } } } while (0)
; __device__ __forceinline__ void xcd_barrier(const XcdBarrier& b, const bool leader) {
;     ...
;         const unsigned old = xb_add(&bar[XB_XSUB(b.x)], 1u);
;         const unsigned gen = old / nloc;
;         if (old + 1u == (gen + 1u) * nloc) {
;             __builtin_amdgcn_fence(__ATOMIC_RELEASE, "agent");
;             asm volatile("s_waitcnt vmcnt(0)" ::: "memory");
;             const unsigned og = xb_add(&bar[XB_TOP], 1u);
;             const unsigned tg = og / nx;
;             if (og + 1u == (tg + 1u) * nx) xb_add(&bar[XB_TOPGEN], 1u);
;             else XB_SPIN(xb_ld(&bar[XB_TOPGEN]) == tg, bar);
;             __builtin_amdgcn_fence(__ATOMIC_ACQUIRE, "agent");
;             xb_add(&bar[XB_XGEN(b.x)], 1u);
;             asm volatile("s_waitcnt vmcnt(0)" ::: "memory");
;         } else {
;             XB_SPIN(xb_ld(&bar[XB_XGEN(b.x)]) == gen, bar);
.LBB0_1198:
	s_or_b64 exec, exec, s[10:11]
	v_cvt_f32_u32_e32 v4, v2
	s_waitcnt vmcnt(0)
	v_readfirstlane_b32 s0, v3
	v_sub_u32_e32 v3, 0, v2
	v_rcp_iflag_f32_e32 v4, v4
	v_add_u32_e32 v5, s0, v1
	v_mul_f32_e32 v4, 0x4f7ffffe, v4
	v_cvt_u32_f32_e32 v4, v4
	v_mul_lo_u32 v1, v3, v4
	v_mul_hi_u32 v1, v4, v1
	v_add_u32_e32 v1, v4, v1
	v_mul_hi_u32 v1, v5, v1
	v_mul_lo_u32 v3, v1, v2
	v_sub_u32_e32 v3, v5, v3
	v_add_u32_e32 v4, 1, v1
	v_cmp_ge_u32_e32 vcc, v3, v2
	s_nop 1
	v_cndmask_b32_e32 v1, v1, v4, vcc
	v_sub_u32_e32 v4, v3, v2
	v_cndmask_b32_e32 v3, v3, v4, vcc
	v_add_u32_e32 v4, 1, v1
	v_cmp_ge_u32_e32 vcc, v3, v2
	v_add_u32_e32 v3, 1, v5
	s_nop 0
	v_cndmask_b32_e32 v1, v1, v4, vcc
	v_mul_lo_u32 v4, v2, v1
	v_add_u32_e32 v2, v4, v2
	v_add_u32_e32 v4, 1, v4
	v_cmp_eq_u32_e32 vcc, v3, v4
	s_cbranch_vccz .Lewb_10
	buffer_wbl2 sc1
.Lewb_10:
	v_cmp_ne_u32_e32 vcc, v3, v2
	s_and_saveexec_b64 s[0:1], vcc
	s_xor_b64 s[8:9], exec, s[0:1]
	s_cbranch_execz .LBB0_1212
	s_waitcnt lgkmcnt(0)
	v_mov_b32_e32 v0, 0x2000
	s_load_dwordx2 s[14:15], s[90:91], 0xb0
	s_waitcnt lgkmcnt(0)
	s_add_u32 s14, s14, 0x1d79b500
	s_addc_u32 s15, s15, 0
	v_mov_b32_e32 v0, 0
	global_load_dword v0, v0, s[14:15] sc1
	s_waitcnt vmcnt(0)
	v_cmp_eq_u32_e32 vcc, v0, v1
	s_and_saveexec_b64 s[10:11], vcc
	s_cbranch_execz .LBB0_1211
	s_add_u32 s12, s4, 0x1d798200
	s_addc_u32 s13, s5, 0
	s_mov_b32 s0, 1
	s_mov_b64 s[16:17], 0
	v_mov_b32_e32 v0, 0
	s_branch .LBB0_1202
